# software-pipelined prenorm_rows (gains hoisted out of the row loop, counted vmcnt) + Epi3 exchange keeps residual prefetch in flight
# speedup vs baseline: 1.0215x; 1.0052x over previous
.LBB0_297:
	s_or_b64 exec, exec, s[2:3]
	v_mov_b32_e32 v0, v216
	s_mov_b64 s[0:1], 0x5800000
	v_and_b32_e32 v4, 63, v0
	v_ashrrev_i32_e32 v5, 6, v0
	v_xor_b32_e32 v0, 1, v219
	v_cmp_lt_i32_e32 vcc, v0, v223
	s_mov_b32 s2, 0
	s_nop 0
	v_cndmask_b32_e32 v0, v219, v0, vcc
	v_lshlrev_b32_e32 v14, 2, v0
	v_xor_b32_e32 v0, 2, v219
	v_cmp_lt_i32_e32 vcc, v0, v223
	s_nop 1
	v_cndmask_b32_e32 v0, v219, v0, vcc
	v_lshlrev_b32_e32 v15, 2, v0
	v_xor_b32_e32 v0, 4, v219
	v_cmp_lt_i32_e32 vcc, v0, v223
	s_nop 1
	v_cndmask_b32_e32 v0, v219, v0, vcc
	v_lshlrev_b32_e32 v16, 2, v0
	v_xor_b32_e32 v0, 8, v219
	v_cmp_lt_i32_e32 vcc, v0, v223
	s_nop 1
	v_cndmask_b32_e32 v0, v219, v0, vcc
	v_cmp_lt_i32_e32 vcc, v221, v223
	v_lshlrev_b32_e32 v17, 2, v0
	s_nop 0
	v_cndmask_b32_e32 v0, v219, v221, vcc
	v_cmp_lt_i32_e32 vcc, v224, v223
	v_lshlrev_b32_e32 v18, 2, v0
	s_nop 0
	v_cndmask_b32_e32 v0, v219, v224, vcc
	v_lshlrev_b32_e32 v19, 2, v0
	v_lshlrev_b32_e32 v0, 3, v4
	v_lshl_add_u64 v[2:3], s[82:83], 0, v[0:1]
	v_lshl_add_u64 v[6:7], v[2:3], 0, s[0:1]
	s_mov_b64 s[0:1], 0x1b000000
	v_lshl_add_u64 v[12:13], v[2:3], 0, s[0:1]
	v_readlane_b32 s0, v253, 19
	v_readlane_b32 s1, v253, 21
	s_lshl_b32 s0, s0, 8
	s_lshl_b32 s1, s1, 6
	v_lshlrev_b32_e32 v0, 4, v4
	s_add_i32 s1, s1, s0
	v_readlane_b32 s0, v253, 24
	v_lshl_add_u64 v[8:9], s[52:53], 0, v[0:1]
	v_lshl_add_u64 v[10:11], s[58:59], 0, v[0:1]
	v_add_u32_e32 v0, s1, v5
	s_lshl_b32 s0, s0, 8
	v_subrev_u32_e32 v0, s0, v0
	v_readlane_b32 s0, v253, 20
	s_lshl_b32 s0, s0, 6
	s_nop 0
	v_subrev_u32_e32 v0, s0, v0
	v_readlane_b32 s0, v253, 32
	s_nop 1
	v_subrev_u32_e32 v0, s0, v0
	v_mov_b64_e32 v[134:135], v[8:9]
	v_mov_b64_e32 v[136:137], v[12:13]
	global_load_dwordx4 v[64:67], v[10:11], off offset:0
	global_load_dwordx4 v[68:71], v[10:11], off offset:1024
	global_load_dwordx4 v[72:75], v[10:11], off offset:2048
	global_load_dwordx4 v[76:79], v[10:11], off offset:3072
	v_mov_b32_e32 v132, v0
	v_ashrrev_i32_e32 v133, 31, v132
	v_lshlrev_b64 v[138:139], 12, v[132:133]
	v_lshl_add_u64 v[2:3], v[134:135], 0, v[138:139]
	global_load_dwordx4 v[80:83], v[2:3], off offset:0
	global_load_dwordx4 v[84:87], v[2:3], off offset:1024
	global_load_dwordx4 v[88:91], v[2:3], off offset:2048
	global_load_dwordx4 v[92:95], v[2:3], off offset:3072
	v_add_u32_e32 v132, 8, v0
	v_ashrrev_i32_e32 v133, 31, v132
	v_lshlrev_b64 v[138:139], 12, v[132:133]
	v_lshl_add_u64 v[2:3], v[134:135], 0, v[138:139]
	global_load_dwordx4 v[96:99], v[2:3], off offset:0
	global_load_dwordx4 v[100:103], v[2:3], off offset:1024
	global_load_dwordx4 v[104:107], v[2:3], off offset:2048
	global_load_dwordx4 v[108:111], v[2:3], off offset:3072
	v_mov_b32_e32 v132, v0
	v_ashrrev_i32_e32 v133, 31, v132
	v_lshlrev_b64 v[138:139], 11, v[132:133]
	v_lshl_add_u64 v[128:129], v[6:7], 0, v[138:139]
	v_lshl_add_u64 v[130:131], v[136:137], 0, v[138:139]
	s_waitcnt vmcnt(4)
	v_mul_f32_e32 v112, v81, v81
	v_mul_f32_e32 v113, v85, v85
	v_mul_f32_e32 v114, v89, v89
	v_mul_f32_e32 v115, v93, v93
	v_fmac_f32_e32 v112, v80, v80
	v_fmac_f32_e32 v113, v84, v84
	v_fmac_f32_e32 v114, v88, v88
	v_fmac_f32_e32 v115, v92, v92
	v_fmac_f32_e32 v112, v82, v82
	v_fmac_f32_e32 v113, v86, v86
	v_fmac_f32_e32 v114, v90, v90
	v_fmac_f32_e32 v115, v94, v94
	v_fmac_f32_e32 v112, v83, v83
	v_fmac_f32_e32 v113, v87, v87
	v_fmac_f32_e32 v114, v91, v91
	v_fmac_f32_e32 v115, v95, v95
	v_add_f32_e32 v116, v112, v113
	v_add_f32_e32 v116, v116, v114
	v_add_f32_e32 v116, v116, v115
	ds_bpermute_b32 v117, v14, v116
	s_waitcnt lgkmcnt(0)
	v_add_f32_e32 v116, v116, v117
	ds_bpermute_b32 v117, v15, v116
	s_waitcnt lgkmcnt(0)
	v_add_f32_e32 v116, v116, v117
	ds_bpermute_b32 v117, v16, v116
	s_waitcnt lgkmcnt(0)
	v_add_f32_e32 v116, v116, v117
	ds_bpermute_b32 v117, v17, v116
	s_waitcnt lgkmcnt(0)
	v_add_f32_e32 v116, v116, v117
	ds_bpermute_b32 v117, v18, v116
	s_waitcnt lgkmcnt(0)
	v_add_f32_e32 v116, v116, v117
	ds_bpermute_b32 v117, v19, v116
	s_waitcnt lgkmcnt(0)
	v_add_f32_e32 v116, v116, v117
	v_fmamk_f32 v116, v116, 0x3a800000, v217
	v_mul_f32_e32 v117, 0x4f800000, v116
	v_cmp_gt_f32_e32 vcc, s36, v116
	s_nop 1
	v_cndmask_b32_e32 v116, v116, v117, vcc
	v_sqrt_f32_e32 v117, v116
	s_nop 0
	v_add_u32_e32 v118, -1, v117
	v_add_u32_e32 v119, 1, v117
	v_fma_f32 v120, -v118, v117, v116
	v_fma_f32 v121, -v119, v117, v116
	v_cmp_ge_f32_e64 s[0:1], 0, v120
	s_nop 1
	v_cndmask_b32_e64 v117, v117, v118, s[0:1]
	v_cmp_lt_f32_e64 s[0:1], 0, v121
	s_nop 1
	v_cndmask_b32_e64 v117, v117, v119, s[0:1]
	v_mul_f32_e32 v118, 0x37800000, v117
	v_cndmask_b32_e32 v117, v117, v118, vcc
	v_cmp_class_f32_e32 vcc, v116, v218
	s_nop 1
	v_cndmask_b32_e32 v116, v117, v116, vcc
	v_div_scale_f32 v117, s[0:1], v116, v116, 1.0
	v_rcp_f32_e32 v119, v117
	v_div_scale_f32 v118, vcc, 1.0, v116, 1.0
	v_fma_f32 v120, -v117, v119, 1.0
	v_fmac_f32_e32 v119, v120, v119
	v_mul_f32_e32 v120, v118, v119
	v_fma_f32 v121, -v117, v120, v118
	v_fmac_f32_e32 v120, v121, v119
	v_fma_f32 v117, -v117, v120, v118
	v_div_fmas_f32 v117, v117, v119, v120
	v_div_fixup_f32 v122, v117, v116, 1.0
	v_cvt_pk_bf16_f32 v126, v80, v81
	v_cvt_pk_bf16_f32 v127, v82, v83
	global_store_dwordx2 v[130:131], v[126:127], off offset:0
	v_mul_f32_e32 v80, v80, v122
	v_mul_f32_e32 v81, v81, v122
	v_mul_f32_e32 v82, v82, v122
	v_mul_f32_e32 v83, v83, v122
	v_mul_f32_e32 v80, v64, v80
	v_mul_f32_e32 v81, v65, v81
	v_mul_f32_e32 v82, v66, v82
	v_mul_f32_e32 v83, v67, v83
	v_cvt_pk_bf16_f32 v124, v80, v81
	v_cvt_pk_bf16_f32 v125, v82, v83
	global_store_dwordx2 v[128:129], v[124:125], off offset:0
	v_cvt_pk_bf16_f32 v126, v84, v85
	v_cvt_pk_bf16_f32 v127, v86, v87
	global_store_dwordx2 v[130:131], v[126:127], off offset:512
	v_mul_f32_e32 v84, v84, v122
	v_mul_f32_e32 v85, v85, v122
	v_mul_f32_e32 v86, v86, v122
	v_mul_f32_e32 v87, v87, v122
	v_mul_f32_e32 v84, v68, v84
	v_mul_f32_e32 v85, v69, v85
	v_mul_f32_e32 v86, v70, v86
	v_mul_f32_e32 v87, v71, v87
	v_cvt_pk_bf16_f32 v124, v84, v85
	v_cvt_pk_bf16_f32 v125, v86, v87
	global_store_dwordx2 v[128:129], v[124:125], off offset:512
	v_cvt_pk_bf16_f32 v126, v88, v89
	v_cvt_pk_bf16_f32 v127, v90, v91
	global_store_dwordx2 v[130:131], v[126:127], off offset:1024
	v_mul_f32_e32 v88, v88, v122
	v_mul_f32_e32 v89, v89, v122
	v_mul_f32_e32 v90, v90, v122
	v_mul_f32_e32 v91, v91, v122
	v_mul_f32_e32 v88, v72, v88
	v_mul_f32_e32 v89, v73, v89
	v_mul_f32_e32 v90, v74, v90
	v_mul_f32_e32 v91, v75, v91
	v_cvt_pk_bf16_f32 v124, v88, v89
	v_cvt_pk_bf16_f32 v125, v90, v91
	global_store_dwordx2 v[128:129], v[124:125], off offset:1024
	v_cvt_pk_bf16_f32 v126, v92, v93
	v_cvt_pk_bf16_f32 v127, v94, v95
	global_store_dwordx2 v[130:131], v[126:127], off offset:1536
	v_mul_f32_e32 v92, v92, v122
	v_mul_f32_e32 v93, v93, v122
	v_mul_f32_e32 v94, v94, v122
	v_mul_f32_e32 v95, v95, v122
	v_mul_f32_e32 v92, v76, v92
	v_mul_f32_e32 v93, v77, v93
	v_mul_f32_e32 v94, v78, v94
	v_mul_f32_e32 v95, v79, v95
	v_cvt_pk_bf16_f32 v124, v92, v93
	v_cvt_pk_bf16_f32 v125, v94, v95
	global_store_dwordx2 v[128:129], v[124:125], off offset:1536
	v_add_u32_e32 v132, 16, v0
	v_ashrrev_i32_e32 v133, 31, v132
	v_lshlrev_b64 v[138:139], 12, v[132:133]
	v_lshl_add_u64 v[2:3], v[134:135], 0, v[138:139]
	global_load_dwordx4 v[80:83], v[2:3], off offset:0
	global_load_dwordx4 v[84:87], v[2:3], off offset:1024
	global_load_dwordx4 v[88:91], v[2:3], off offset:2048
	global_load_dwordx4 v[92:95], v[2:3], off offset:3072
	v_add_u32_e32 v132, 8, v0
	v_ashrrev_i32_e32 v133, 31, v132
	v_lshlrev_b64 v[138:139], 11, v[132:133]
	v_lshl_add_u64 v[128:129], v[6:7], 0, v[138:139]
	v_lshl_add_u64 v[130:131], v[136:137], 0, v[138:139]
	s_waitcnt vmcnt(12)
	v_mul_f32_e32 v112, v97, v97
	v_mul_f32_e32 v113, v101, v101
	v_mul_f32_e32 v114, v105, v105
	v_mul_f32_e32 v115, v109, v109
	v_fmac_f32_e32 v112, v96, v96
	v_fmac_f32_e32 v113, v100, v100
	v_fmac_f32_e32 v114, v104, v104
	v_fmac_f32_e32 v115, v108, v108
	v_fmac_f32_e32 v112, v98, v98
	v_fmac_f32_e32 v113, v102, v102
	v_fmac_f32_e32 v114, v106, v106
	v_fmac_f32_e32 v115, v110, v110
	v_fmac_f32_e32 v112, v99, v99
	v_fmac_f32_e32 v113, v103, v103
	v_fmac_f32_e32 v114, v107, v107
	v_fmac_f32_e32 v115, v111, v111
	v_add_f32_e32 v116, v112, v113
	v_add_f32_e32 v116, v116, v114
	v_add_f32_e32 v116, v116, v115
	ds_bpermute_b32 v117, v14, v116
	s_waitcnt lgkmcnt(0)
	v_add_f32_e32 v116, v116, v117
	ds_bpermute_b32 v117, v15, v116
	s_waitcnt lgkmcnt(0)
	v_add_f32_e32 v116, v116, v117
	ds_bpermute_b32 v117, v16, v116
	s_waitcnt lgkmcnt(0)
	v_add_f32_e32 v116, v116, v117
	ds_bpermute_b32 v117, v17, v116
	s_waitcnt lgkmcnt(0)
	v_add_f32_e32 v116, v116, v117
	ds_bpermute_b32 v117, v18, v116
	s_waitcnt lgkmcnt(0)
	v_add_f32_e32 v116, v116, v117
	ds_bpermute_b32 v117, v19, v116
	s_waitcnt lgkmcnt(0)
	v_add_f32_e32 v116, v116, v117
	v_fmamk_f32 v116, v116, 0x3a800000, v217
	v_mul_f32_e32 v117, 0x4f800000, v116
	v_cmp_gt_f32_e32 vcc, s36, v116
	s_nop 1
	v_cndmask_b32_e32 v116, v116, v117, vcc
	v_sqrt_f32_e32 v117, v116
	s_nop 0
	v_add_u32_e32 v118, -1, v117
	v_add_u32_e32 v119, 1, v117
	v_fma_f32 v120, -v118, v117, v116
	v_fma_f32 v121, -v119, v117, v116
	v_cmp_ge_f32_e64 s[0:1], 0, v120
	s_nop 1
	v_cndmask_b32_e64 v117, v117, v118, s[0:1]
	v_cmp_lt_f32_e64 s[0:1], 0, v121
	s_nop 1
	v_cndmask_b32_e64 v117, v117, v119, s[0:1]
	v_mul_f32_e32 v118, 0x37800000, v117
	v_cndmask_b32_e32 v117, v117, v118, vcc
	v_cmp_class_f32_e32 vcc, v116, v218
	s_nop 1
	v_cndmask_b32_e32 v116, v117, v116, vcc
	v_div_scale_f32 v117, s[0:1], v116, v116, 1.0
	v_rcp_f32_e32 v119, v117
	v_div_scale_f32 v118, vcc, 1.0, v116, 1.0
	v_fma_f32 v120, -v117, v119, 1.0
	v_fmac_f32_e32 v119, v120, v119
	v_mul_f32_e32 v120, v118, v119
	v_fma_f32 v121, -v117, v120, v118
	v_fmac_f32_e32 v120, v121, v119
	v_fma_f32 v117, -v117, v120, v118
	v_div_fmas_f32 v117, v117, v119, v120
	v_div_fixup_f32 v122, v117, v116, 1.0
	v_cvt_pk_bf16_f32 v126, v96, v97
	v_cvt_pk_bf16_f32 v127, v98, v99
	global_store_dwordx2 v[130:131], v[126:127], off offset:0
	v_mul_f32_e32 v96, v96, v122
	v_mul_f32_e32 v97, v97, v122
	v_mul_f32_e32 v98, v98, v122
	v_mul_f32_e32 v99, v99, v122
	v_mul_f32_e32 v96, v64, v96
	v_mul_f32_e32 v97, v65, v97
	v_mul_f32_e32 v98, v66, v98
	v_mul_f32_e32 v99, v67, v99
	v_cvt_pk_bf16_f32 v124, v96, v97
	v_cvt_pk_bf16_f32 v125, v98, v99
	global_store_dwordx2 v[128:129], v[124:125], off offset:0
	v_cvt_pk_bf16_f32 v126, v100, v101
	v_cvt_pk_bf16_f32 v127, v102, v103
	global_store_dwordx2 v[130:131], v[126:127], off offset:512
	v_mul_f32_e32 v100, v100, v122
	v_mul_f32_e32 v101, v101, v122
	v_mul_f32_e32 v102, v102, v122
	v_mul_f32_e32 v103, v103, v122
	v_mul_f32_e32 v100, v68, v100
	v_mul_f32_e32 v101, v69, v101
	v_mul_f32_e32 v102, v70, v102
	v_mul_f32_e32 v103, v71, v103
	v_cvt_pk_bf16_f32 v124, v100, v101
	v_cvt_pk_bf16_f32 v125, v102, v103
	global_store_dwordx2 v[128:129], v[124:125], off offset:512
	v_cvt_pk_bf16_f32 v126, v104, v105
	v_cvt_pk_bf16_f32 v127, v106, v107
	global_store_dwordx2 v[130:131], v[126:127], off offset:1024
	v_mul_f32_e32 v104, v104, v122
	v_mul_f32_e32 v105, v105, v122
	v_mul_f32_e32 v106, v106, v122
	v_mul_f32_e32 v107, v107, v122
	v_mul_f32_e32 v104, v72, v104
	v_mul_f32_e32 v105, v73, v105
	v_mul_f32_e32 v106, v74, v106
	v_mul_f32_e32 v107, v75, v107
	v_cvt_pk_bf16_f32 v124, v104, v105
	v_cvt_pk_bf16_f32 v125, v106, v107
	global_store_dwordx2 v[128:129], v[124:125], off offset:1024
	v_cvt_pk_bf16_f32 v126, v108, v109
	v_cvt_pk_bf16_f32 v127, v110, v111
	global_store_dwordx2 v[130:131], v[126:127], off offset:1536
	v_mul_f32_e32 v108, v108, v122
	v_mul_f32_e32 v109, v109, v122
	v_mul_f32_e32 v110, v110, v122
	v_mul_f32_e32 v111, v111, v122
	v_mul_f32_e32 v108, v76, v108
	v_mul_f32_e32 v109, v77, v109
	v_mul_f32_e32 v110, v78, v110
	v_mul_f32_e32 v111, v79, v111
	v_cvt_pk_bf16_f32 v124, v108, v109
	v_cvt_pk_bf16_f32 v125, v110, v111
	global_store_dwordx2 v[128:129], v[124:125], off offset:1536
	v_add_u32_e32 v132, 24, v0
	v_ashrrev_i32_e32 v133, 31, v132
	v_lshlrev_b64 v[138:139], 12, v[132:133]
	v_lshl_add_u64 v[2:3], v[134:135], 0, v[138:139]
	global_load_dwordx4 v[96:99], v[2:3], off offset:0
	global_load_dwordx4 v[100:103], v[2:3], off offset:1024
	global_load_dwordx4 v[104:107], v[2:3], off offset:2048
	global_load_dwordx4 v[108:111], v[2:3], off offset:3072
	v_add_u32_e32 v132, 16, v0
	v_ashrrev_i32_e32 v133, 31, v132
	v_lshlrev_b64 v[138:139], 11, v[132:133]
	v_lshl_add_u64 v[128:129], v[6:7], 0, v[138:139]
	v_lshl_add_u64 v[130:131], v[136:137], 0, v[138:139]
	s_waitcnt vmcnt(12)
	v_mul_f32_e32 v112, v81, v81
	v_mul_f32_e32 v113, v85, v85
	v_mul_f32_e32 v114, v89, v89
	v_mul_f32_e32 v115, v93, v93
	v_fmac_f32_e32 v112, v80, v80
	v_fmac_f32_e32 v113, v84, v84
	v_fmac_f32_e32 v114, v88, v88
	v_fmac_f32_e32 v115, v92, v92
	v_fmac_f32_e32 v112, v82, v82
	v_fmac_f32_e32 v113, v86, v86
	v_fmac_f32_e32 v114, v90, v90
	v_fmac_f32_e32 v115, v94, v94
	v_fmac_f32_e32 v112, v83, v83
	v_fmac_f32_e32 v113, v87, v87
	v_fmac_f32_e32 v114, v91, v91
	v_fmac_f32_e32 v115, v95, v95
	v_add_f32_e32 v116, v112, v113
	v_add_f32_e32 v116, v116, v114
	v_add_f32_e32 v116, v116, v115
	ds_bpermute_b32 v117, v14, v116
	s_waitcnt lgkmcnt(0)
	v_add_f32_e32 v116, v116, v117
	ds_bpermute_b32 v117, v15, v116
	s_waitcnt lgkmcnt(0)
	v_add_f32_e32 v116, v116, v117
	ds_bpermute_b32 v117, v16, v116
	s_waitcnt lgkmcnt(0)
	v_add_f32_e32 v116, v116, v117
	ds_bpermute_b32 v117, v17, v116
	s_waitcnt lgkmcnt(0)
	v_add_f32_e32 v116, v116, v117
	ds_bpermute_b32 v117, v18, v116
	s_waitcnt lgkmcnt(0)
	v_add_f32_e32 v116, v116, v117
	ds_bpermute_b32 v117, v19, v116
	s_waitcnt lgkmcnt(0)
	v_add_f32_e32 v116, v116, v117
	v_fmamk_f32 v116, v116, 0x3a800000, v217
	v_mul_f32_e32 v117, 0x4f800000, v116
	v_cmp_gt_f32_e32 vcc, s36, v116
	s_nop 1
	v_cndmask_b32_e32 v116, v116, v117, vcc
	v_sqrt_f32_e32 v117, v116
	s_nop 0
	v_add_u32_e32 v118, -1, v117
	v_add_u32_e32 v119, 1, v117
	v_fma_f32 v120, -v118, v117, v116
	v_fma_f32 v121, -v119, v117, v116
	v_cmp_ge_f32_e64 s[0:1], 0, v120
	s_nop 1
	v_cndmask_b32_e64 v117, v117, v118, s[0:1]
	v_cmp_lt_f32_e64 s[0:1], 0, v121
	s_nop 1
	v_cndmask_b32_e64 v117, v117, v119, s[0:1]
	v_mul_f32_e32 v118, 0x37800000, v117
	v_cndmask_b32_e32 v117, v117, v118, vcc
	v_cmp_class_f32_e32 vcc, v116, v218
	s_nop 1
	v_cndmask_b32_e32 v116, v117, v116, vcc
	v_div_scale_f32 v117, s[0:1], v116, v116, 1.0
	v_rcp_f32_e32 v119, v117
	v_div_scale_f32 v118, vcc, 1.0, v116, 1.0
	v_fma_f32 v120, -v117, v119, 1.0
	v_fmac_f32_e32 v119, v120, v119
	v_mul_f32_e32 v120, v118, v119
	v_fma_f32 v121, -v117, v120, v118
	v_fmac_f32_e32 v120, v121, v119
	v_fma_f32 v117, -v117, v120, v118
	v_div_fmas_f32 v117, v117, v119, v120
	v_div_fixup_f32 v122, v117, v116, 1.0
	v_cvt_pk_bf16_f32 v126, v80, v81
	v_cvt_pk_bf16_f32 v127, v82, v83
	global_store_dwordx2 v[130:131], v[126:127], off offset:0
	v_mul_f32_e32 v80, v80, v122
	v_mul_f32_e32 v81, v81, v122
	v_mul_f32_e32 v82, v82, v122
	v_mul_f32_e32 v83, v83, v122
	v_mul_f32_e32 v80, v64, v80
	v_mul_f32_e32 v81, v65, v81
	v_mul_f32_e32 v82, v66, v82
	v_mul_f32_e32 v83, v67, v83
	v_cvt_pk_bf16_f32 v124, v80, v81
	v_cvt_pk_bf16_f32 v125, v82, v83
	global_store_dwordx2 v[128:129], v[124:125], off offset:0
	v_cvt_pk_bf16_f32 v126, v84, v85
	v_cvt_pk_bf16_f32 v127, v86, v87
	global_store_dwordx2 v[130:131], v[126:127], off offset:512
	v_mul_f32_e32 v84, v84, v122
	v_mul_f32_e32 v85, v85, v122
	v_mul_f32_e32 v86, v86, v122
	v_mul_f32_e32 v87, v87, v122
	v_mul_f32_e32 v84, v68, v84
	v_mul_f32_e32 v85, v69, v85
	v_mul_f32_e32 v86, v70, v86
	v_mul_f32_e32 v87, v71, v87
	v_cvt_pk_bf16_f32 v124, v84, v85
	v_cvt_pk_bf16_f32 v125, v86, v87
	global_store_dwordx2 v[128:129], v[124:125], off offset:512
	v_cvt_pk_bf16_f32 v126, v88, v89
	v_cvt_pk_bf16_f32 v127, v90, v91
	global_store_dwordx2 v[130:131], v[126:127], off offset:1024
	v_mul_f32_e32 v88, v88, v122
	v_mul_f32_e32 v89, v89, v122
	v_mul_f32_e32 v90, v90, v122
	v_mul_f32_e32 v91, v91, v122
	v_mul_f32_e32 v88, v72, v88
	v_mul_f32_e32 v89, v73, v89
	v_mul_f32_e32 v90, v74, v90
	v_mul_f32_e32 v91, v75, v91
	v_cvt_pk_bf16_f32 v124, v88, v89
	v_cvt_pk_bf16_f32 v125, v90, v91
	global_store_dwordx2 v[128:129], v[124:125], off offset:1024
	v_cvt_pk_bf16_f32 v126, v92, v93
	v_cvt_pk_bf16_f32 v127, v94, v95
	global_store_dwordx2 v[130:131], v[126:127], off offset:1536
	v_mul_f32_e32 v92, v92, v122
	v_mul_f32_e32 v93, v93, v122
	v_mul_f32_e32 v94, v94, v122
	v_mul_f32_e32 v95, v95, v122
	v_mul_f32_e32 v92, v76, v92
	v_mul_f32_e32 v93, v77, v93
	v_mul_f32_e32 v94, v78, v94
	v_mul_f32_e32 v95, v79, v95
	v_cvt_pk_bf16_f32 v124, v92, v93
	v_cvt_pk_bf16_f32 v125, v94, v95
	global_store_dwordx2 v[128:129], v[124:125], off offset:1536
	v_add_u32_e32 v132, 32, v0
	v_ashrrev_i32_e32 v133, 31, v132
	v_lshlrev_b64 v[138:139], 12, v[132:133]
	v_lshl_add_u64 v[2:3], v[134:135], 0, v[138:139]
	global_load_dwordx4 v[80:83], v[2:3], off offset:0
	global_load_dwordx4 v[84:87], v[2:3], off offset:1024
	global_load_dwordx4 v[88:91], v[2:3], off offset:2048
	global_load_dwordx4 v[92:95], v[2:3], off offset:3072
	v_add_u32_e32 v132, 24, v0
	v_ashrrev_i32_e32 v133, 31, v132
	v_lshlrev_b64 v[138:139], 11, v[132:133]
	v_lshl_add_u64 v[128:129], v[6:7], 0, v[138:139]
	v_lshl_add_u64 v[130:131], v[136:137], 0, v[138:139]
	s_waitcnt vmcnt(12)
	v_mul_f32_e32 v112, v97, v97
	v_mul_f32_e32 v113, v101, v101
	v_mul_f32_e32 v114, v105, v105
	v_mul_f32_e32 v115, v109, v109
	v_fmac_f32_e32 v112, v96, v96
	v_fmac_f32_e32 v113, v100, v100
	v_fmac_f32_e32 v114, v104, v104
	v_fmac_f32_e32 v115, v108, v108
	v_fmac_f32_e32 v112, v98, v98
	v_fmac_f32_e32 v113, v102, v102
	v_fmac_f32_e32 v114, v106, v106
	v_fmac_f32_e32 v115, v110, v110
	v_fmac_f32_e32 v112, v99, v99
	v_fmac_f32_e32 v113, v103, v103
	v_fmac_f32_e32 v114, v107, v107
	v_fmac_f32_e32 v115, v111, v111
	v_add_f32_e32 v116, v112, v113
	v_add_f32_e32 v116, v116, v114
	v_add_f32_e32 v116, v116, v115
	ds_bpermute_b32 v117, v14, v116
	s_waitcnt lgkmcnt(0)
	v_add_f32_e32 v116, v116, v117
	ds_bpermute_b32 v117, v15, v116
	s_waitcnt lgkmcnt(0)
	v_add_f32_e32 v116, v116, v117
	ds_bpermute_b32 v117, v16, v116
	s_waitcnt lgkmcnt(0)
	v_add_f32_e32 v116, v116, v117
	ds_bpermute_b32 v117, v17, v116
	s_waitcnt lgkmcnt(0)
	v_add_f32_e32 v116, v116, v117
	ds_bpermute_b32 v117, v18, v116
	s_waitcnt lgkmcnt(0)
	v_add_f32_e32 v116, v116, v117
	ds_bpermute_b32 v117, v19, v116
	s_waitcnt lgkmcnt(0)
	v_add_f32_e32 v116, v116, v117
	v_fmamk_f32 v116, v116, 0x3a800000, v217
	v_mul_f32_e32 v117, 0x4f800000, v116
	v_cmp_gt_f32_e32 vcc, s36, v116
	s_nop 1
	v_cndmask_b32_e32 v116, v116, v117, vcc
	v_sqrt_f32_e32 v117, v116
	s_nop 0
	v_add_u32_e32 v118, -1, v117
	v_add_u32_e32 v119, 1, v117
	v_fma_f32 v120, -v118, v117, v116
	v_fma_f32 v121, -v119, v117, v116
	v_cmp_ge_f32_e64 s[0:1], 0, v120
	s_nop 1
	v_cndmask_b32_e64 v117, v117, v118, s[0:1]
	v_cmp_lt_f32_e64 s[0:1], 0, v121
	s_nop 1
	v_cndmask_b32_e64 v117, v117, v119, s[0:1]
	v_mul_f32_e32 v118, 0x37800000, v117
	v_cndmask_b32_e32 v117, v117, v118, vcc
	v_cmp_class_f32_e32 vcc, v116, v218
	s_nop 1
	v_cndmask_b32_e32 v116, v117, v116, vcc
	v_div_scale_f32 v117, s[0:1], v116, v116, 1.0
	v_rcp_f32_e32 v119, v117
	v_div_scale_f32 v118, vcc, 1.0, v116, 1.0
	v_fma_f32 v120, -v117, v119, 1.0
	v_fmac_f32_e32 v119, v120, v119
	v_mul_f32_e32 v120, v118, v119
	v_fma_f32 v121, -v117, v120, v118
	v_fmac_f32_e32 v120, v121, v119
	v_fma_f32 v117, -v117, v120, v118
	v_div_fmas_f32 v117, v117, v119, v120
	v_div_fixup_f32 v122, v117, v116, 1.0
	v_cvt_pk_bf16_f32 v126, v96, v97
	v_cvt_pk_bf16_f32 v127, v98, v99
	global_store_dwordx2 v[130:131], v[126:127], off offset:0
	v_mul_f32_e32 v96, v96, v122
	v_mul_f32_e32 v97, v97, v122
	v_mul_f32_e32 v98, v98, v122
	v_mul_f32_e32 v99, v99, v122
	v_mul_f32_e32 v96, v64, v96
	v_mul_f32_e32 v97, v65, v97
	v_mul_f32_e32 v98, v66, v98
	v_mul_f32_e32 v99, v67, v99
	v_cvt_pk_bf16_f32 v124, v96, v97
	v_cvt_pk_bf16_f32 v125, v98, v99
	global_store_dwordx2 v[128:129], v[124:125], off offset:0
	v_cvt_pk_bf16_f32 v126, v100, v101
	v_cvt_pk_bf16_f32 v127, v102, v103
	global_store_dwordx2 v[130:131], v[126:127], off offset:512
	v_mul_f32_e32 v100, v100, v122
	v_mul_f32_e32 v101, v101, v122
	v_mul_f32_e32 v102, v102, v122
	v_mul_f32_e32 v103, v103, v122
	v_mul_f32_e32 v100, v68, v100
	v_mul_f32_e32 v101, v69, v101
	v_mul_f32_e32 v102, v70, v102
	v_mul_f32_e32 v103, v71, v103
	v_cvt_pk_bf16_f32 v124, v100, v101
	v_cvt_pk_bf16_f32 v125, v102, v103
	global_store_dwordx2 v[128:129], v[124:125], off offset:512
	v_cvt_pk_bf16_f32 v126, v104, v105
	v_cvt_pk_bf16_f32 v127, v106, v107
	global_store_dwordx2 v[130:131], v[126:127], off offset:1024
	v_mul_f32_e32 v104, v104, v122
	v_mul_f32_e32 v105, v105, v122
	v_mul_f32_e32 v106, v106, v122
	v_mul_f32_e32 v107, v107, v122
	v_mul_f32_e32 v104, v72, v104
	v_mul_f32_e32 v105, v73, v105
	v_mul_f32_e32 v106, v74, v106
	v_mul_f32_e32 v107, v75, v107
	v_cvt_pk_bf16_f32 v124, v104, v105
	v_cvt_pk_bf16_f32 v125, v106, v107
	global_store_dwordx2 v[128:129], v[124:125], off offset:1024
	v_cvt_pk_bf16_f32 v126, v108, v109
	v_cvt_pk_bf16_f32 v127, v110, v111
	global_store_dwordx2 v[130:131], v[126:127], off offset:1536
	v_mul_f32_e32 v108, v108, v122
	v_mul_f32_e32 v109, v109, v122
	v_mul_f32_e32 v110, v110, v122
	v_mul_f32_e32 v111, v111, v122
	v_mul_f32_e32 v108, v76, v108
	v_mul_f32_e32 v109, v77, v109
	v_mul_f32_e32 v110, v78, v110
	v_mul_f32_e32 v111, v79, v111
	v_cvt_pk_bf16_f32 v124, v108, v109
	v_cvt_pk_bf16_f32 v125, v110, v111
	global_store_dwordx2 v[128:129], v[124:125], off offset:1536
	v_add_u32_e32 v132, 40, v0
	v_ashrrev_i32_e32 v133, 31, v132
	v_lshlrev_b64 v[138:139], 12, v[132:133]
	v_lshl_add_u64 v[2:3], v[134:135], 0, v[138:139]
	global_load_dwordx4 v[96:99], v[2:3], off offset:0
	global_load_dwordx4 v[100:103], v[2:3], off offset:1024
	global_load_dwordx4 v[104:107], v[2:3], off offset:2048
	global_load_dwordx4 v[108:111], v[2:3], off offset:3072
	v_add_u32_e32 v132, 32, v0
	v_ashrrev_i32_e32 v133, 31, v132
	v_lshlrev_b64 v[138:139], 11, v[132:133]
	v_lshl_add_u64 v[128:129], v[6:7], 0, v[138:139]
	v_lshl_add_u64 v[130:131], v[136:137], 0, v[138:139]
	s_waitcnt vmcnt(12)
	v_mul_f32_e32 v112, v81, v81
	v_mul_f32_e32 v113, v85, v85
	v_mul_f32_e32 v114, v89, v89
	v_mul_f32_e32 v115, v93, v93
	v_fmac_f32_e32 v112, v80, v80
	v_fmac_f32_e32 v113, v84, v84
	v_fmac_f32_e32 v114, v88, v88
	v_fmac_f32_e32 v115, v92, v92
	v_fmac_f32_e32 v112, v82, v82
	v_fmac_f32_e32 v113, v86, v86
	v_fmac_f32_e32 v114, v90, v90
	v_fmac_f32_e32 v115, v94, v94
	v_fmac_f32_e32 v112, v83, v83
	v_fmac_f32_e32 v113, v87, v87
	v_fmac_f32_e32 v114, v91, v91
	v_fmac_f32_e32 v115, v95, v95
	v_add_f32_e32 v116, v112, v113
	v_add_f32_e32 v116, v116, v114
	v_add_f32_e32 v116, v116, v115
	ds_bpermute_b32 v117, v14, v116
	s_waitcnt lgkmcnt(0)
	v_add_f32_e32 v116, v116, v117
	ds_bpermute_b32 v117, v15, v116
	s_waitcnt lgkmcnt(0)
	v_add_f32_e32 v116, v116, v117
	ds_bpermute_b32 v117, v16, v116
	s_waitcnt lgkmcnt(0)
	v_add_f32_e32 v116, v116, v117
	ds_bpermute_b32 v117, v17, v116
	s_waitcnt lgkmcnt(0)
	v_add_f32_e32 v116, v116, v117
	ds_bpermute_b32 v117, v18, v116
	s_waitcnt lgkmcnt(0)
	v_add_f32_e32 v116, v116, v117
	ds_bpermute_b32 v117, v19, v116
	s_waitcnt lgkmcnt(0)
	v_add_f32_e32 v116, v116, v117
	v_fmamk_f32 v116, v116, 0x3a800000, v217
	v_mul_f32_e32 v117, 0x4f800000, v116
	v_cmp_gt_f32_e32 vcc, s36, v116
	s_nop 1
	v_cndmask_b32_e32 v116, v116, v117, vcc
	v_sqrt_f32_e32 v117, v116
	s_nop 0
	v_add_u32_e32 v118, -1, v117
	v_add_u32_e32 v119, 1, v117
	v_fma_f32 v120, -v118, v117, v116
	v_fma_f32 v121, -v119, v117, v116
	v_cmp_ge_f32_e64 s[0:1], 0, v120
	s_nop 1
	v_cndmask_b32_e64 v117, v117, v118, s[0:1]
	v_cmp_lt_f32_e64 s[0:1], 0, v121
	s_nop 1
	v_cndmask_b32_e64 v117, v117, v119, s[0:1]
	v_mul_f32_e32 v118, 0x37800000, v117
	v_cndmask_b32_e32 v117, v117, v118, vcc
	v_cmp_class_f32_e32 vcc, v116, v218
	s_nop 1
	v_cndmask_b32_e32 v116, v117, v116, vcc
	v_div_scale_f32 v117, s[0:1], v116, v116, 1.0
	v_rcp_f32_e32 v119, v117
	v_div_scale_f32 v118, vcc, 1.0, v116, 1.0
	v_fma_f32 v120, -v117, v119, 1.0
	v_fmac_f32_e32 v119, v120, v119
	v_mul_f32_e32 v120, v118, v119
	v_fma_f32 v121, -v117, v120, v118
	v_fmac_f32_e32 v120, v121, v119
	v_fma_f32 v117, -v117, v120, v118
	v_div_fmas_f32 v117, v117, v119, v120
	v_div_fixup_f32 v122, v117, v116, 1.0
	v_cvt_pk_bf16_f32 v126, v80, v81
	v_cvt_pk_bf16_f32 v127, v82, v83
	global_store_dwordx2 v[130:131], v[126:127], off offset:0
	v_mul_f32_e32 v80, v80, v122
	v_mul_f32_e32 v81, v81, v122
	v_mul_f32_e32 v82, v82, v122
	v_mul_f32_e32 v83, v83, v122
	v_mul_f32_e32 v80, v64, v80
	v_mul_f32_e32 v81, v65, v81
	v_mul_f32_e32 v82, v66, v82
	v_mul_f32_e32 v83, v67, v83
	v_cvt_pk_bf16_f32 v124, v80, v81
	v_cvt_pk_bf16_f32 v125, v82, v83
	global_store_dwordx2 v[128:129], v[124:125], off offset:0
	v_cvt_pk_bf16_f32 v126, v84, v85
	v_cvt_pk_bf16_f32 v127, v86, v87
	global_store_dwordx2 v[130:131], v[126:127], off offset:512
	v_mul_f32_e32 v84, v84, v122
	v_mul_f32_e32 v85, v85, v122
	v_mul_f32_e32 v86, v86, v122
	v_mul_f32_e32 v87, v87, v122
	v_mul_f32_e32 v84, v68, v84
	v_mul_f32_e32 v85, v69, v85
	v_mul_f32_e32 v86, v70, v86
	v_mul_f32_e32 v87, v71, v87
	v_cvt_pk_bf16_f32 v124, v84, v85
	v_cvt_pk_bf16_f32 v125, v86, v87
	global_store_dwordx2 v[128:129], v[124:125], off offset:512
	v_cvt_pk_bf16_f32 v126, v88, v89
	v_cvt_pk_bf16_f32 v127, v90, v91
	global_store_dwordx2 v[130:131], v[126:127], off offset:1024
	v_mul_f32_e32 v88, v88, v122
	v_mul_f32_e32 v89, v89, v122
	v_mul_f32_e32 v90, v90, v122
	v_mul_f32_e32 v91, v91, v122
	v_mul_f32_e32 v88, v72, v88
	v_mul_f32_e32 v89, v73, v89
	v_mul_f32_e32 v90, v74, v90
	v_mul_f32_e32 v91, v75, v91
	v_cvt_pk_bf16_f32 v124, v88, v89
	v_cvt_pk_bf16_f32 v125, v90, v91
	global_store_dwordx2 v[128:129], v[124:125], off offset:1024
	v_cvt_pk_bf16_f32 v126, v92, v93
	v_cvt_pk_bf16_f32 v127, v94, v95
	global_store_dwordx2 v[130:131], v[126:127], off offset:1536
	v_mul_f32_e32 v92, v92, v122
	v_mul_f32_e32 v93, v93, v122
	v_mul_f32_e32 v94, v94, v122
	v_mul_f32_e32 v95, v95, v122
	v_mul_f32_e32 v92, v76, v92
	v_mul_f32_e32 v93, v77, v93
	v_mul_f32_e32 v94, v78, v94
	v_mul_f32_e32 v95, v79, v95
	v_cvt_pk_bf16_f32 v124, v92, v93
	v_cvt_pk_bf16_f32 v125, v94, v95
	global_store_dwordx2 v[128:129], v[124:125], off offset:1536
	v_add_u32_e32 v132, 48, v0
	v_ashrrev_i32_e32 v133, 31, v132
	v_lshlrev_b64 v[138:139], 12, v[132:133]
	v_lshl_add_u64 v[2:3], v[134:135], 0, v[138:139]
	global_load_dwordx4 v[80:83], v[2:3], off offset:0
	global_load_dwordx4 v[84:87], v[2:3], off offset:1024
	global_load_dwordx4 v[88:91], v[2:3], off offset:2048
	global_load_dwordx4 v[92:95], v[2:3], off offset:3072
	v_add_u32_e32 v132, 40, v0
	v_ashrrev_i32_e32 v133, 31, v132
	v_lshlrev_b64 v[138:139], 11, v[132:133]
	v_lshl_add_u64 v[128:129], v[6:7], 0, v[138:139]
	v_lshl_add_u64 v[130:131], v[136:137], 0, v[138:139]
	s_waitcnt vmcnt(12)
	v_mul_f32_e32 v112, v97, v97
	v_mul_f32_e32 v113, v101, v101
	v_mul_f32_e32 v114, v105, v105
	v_mul_f32_e32 v115, v109, v109
	v_fmac_f32_e32 v112, v96, v96
	v_fmac_f32_e32 v113, v100, v100
	v_fmac_f32_e32 v114, v104, v104
	v_fmac_f32_e32 v115, v108, v108
	v_fmac_f32_e32 v112, v98, v98
	v_fmac_f32_e32 v113, v102, v102
	v_fmac_f32_e32 v114, v106, v106
	v_fmac_f32_e32 v115, v110, v110
	v_fmac_f32_e32 v112, v99, v99
	v_fmac_f32_e32 v113, v103, v103
	v_fmac_f32_e32 v114, v107, v107
	v_fmac_f32_e32 v115, v111, v111
	v_add_f32_e32 v116, v112, v113
	v_add_f32_e32 v116, v116, v114
	v_add_f32_e32 v116, v116, v115
	ds_bpermute_b32 v117, v14, v116
	s_waitcnt lgkmcnt(0)
	v_add_f32_e32 v116, v116, v117
	ds_bpermute_b32 v117, v15, v116
	s_waitcnt lgkmcnt(0)
	v_add_f32_e32 v116, v116, v117
	ds_bpermute_b32 v117, v16, v116
	s_waitcnt lgkmcnt(0)
	v_add_f32_e32 v116, v116, v117
	ds_bpermute_b32 v117, v17, v116
	s_waitcnt lgkmcnt(0)
	v_add_f32_e32 v116, v116, v117
	ds_bpermute_b32 v117, v18, v116
	s_waitcnt lgkmcnt(0)
	v_add_f32_e32 v116, v116, v117
	ds_bpermute_b32 v117, v19, v116
	s_waitcnt lgkmcnt(0)
	v_add_f32_e32 v116, v116, v117
	v_fmamk_f32 v116, v116, 0x3a800000, v217
	v_mul_f32_e32 v117, 0x4f800000, v116
	v_cmp_gt_f32_e32 vcc, s36, v116
	s_nop 1
	v_cndmask_b32_e32 v116, v116, v117, vcc
	v_sqrt_f32_e32 v117, v116
	s_nop 0
	v_add_u32_e32 v118, -1, v117
	v_add_u32_e32 v119, 1, v117
	v_fma_f32 v120, -v118, v117, v116
	v_fma_f32 v121, -v119, v117, v116
	v_cmp_ge_f32_e64 s[0:1], 0, v120
	s_nop 1
	v_cndmask_b32_e64 v117, v117, v118, s[0:1]
	v_cmp_lt_f32_e64 s[0:1], 0, v121
	s_nop 1
	v_cndmask_b32_e64 v117, v117, v119, s[0:1]
	v_mul_f32_e32 v118, 0x37800000, v117
	v_cndmask_b32_e32 v117, v117, v118, vcc
	v_cmp_class_f32_e32 vcc, v116, v218
	s_nop 1
	v_cndmask_b32_e32 v116, v117, v116, vcc
	v_div_scale_f32 v117, s[0:1], v116, v116, 1.0
	v_rcp_f32_e32 v119, v117
	v_div_scale_f32 v118, vcc, 1.0, v116, 1.0
	v_fma_f32 v120, -v117, v119, 1.0
	v_fmac_f32_e32 v119, v120, v119
	v_mul_f32_e32 v120, v118, v119
	v_fma_f32 v121, -v117, v120, v118
	v_fmac_f32_e32 v120, v121, v119
	v_fma_f32 v117, -v117, v120, v118
	v_div_fmas_f32 v117, v117, v119, v120
	v_div_fixup_f32 v122, v117, v116, 1.0
	v_cvt_pk_bf16_f32 v126, v96, v97
	v_cvt_pk_bf16_f32 v127, v98, v99
	global_store_dwordx2 v[130:131], v[126:127], off offset:0
	v_mul_f32_e32 v96, v96, v122
	v_mul_f32_e32 v97, v97, v122
	v_mul_f32_e32 v98, v98, v122
	v_mul_f32_e32 v99, v99, v122
	v_mul_f32_e32 v96, v64, v96
	v_mul_f32_e32 v97, v65, v97
	v_mul_f32_e32 v98, v66, v98
	v_mul_f32_e32 v99, v67, v99
	v_cvt_pk_bf16_f32 v124, v96, v97
	v_cvt_pk_bf16_f32 v125, v98, v99
	global_store_dwordx2 v[128:129], v[124:125], off offset:0
	v_cvt_pk_bf16_f32 v126, v100, v101
	v_cvt_pk_bf16_f32 v127, v102, v103
	global_store_dwordx2 v[130:131], v[126:127], off offset:512
	v_mul_f32_e32 v100, v100, v122
	v_mul_f32_e32 v101, v101, v122
	v_mul_f32_e32 v102, v102, v122
	v_mul_f32_e32 v103, v103, v122
	v_mul_f32_e32 v100, v68, v100
	v_mul_f32_e32 v101, v69, v101
	v_mul_f32_e32 v102, v70, v102
	v_mul_f32_e32 v103, v71, v103
	v_cvt_pk_bf16_f32 v124, v100, v101
	v_cvt_pk_bf16_f32 v125, v102, v103
	global_store_dwordx2 v[128:129], v[124:125], off offset:512
	v_cvt_pk_bf16_f32 v126, v104, v105
	v_cvt_pk_bf16_f32 v127, v106, v107
	global_store_dwordx2 v[130:131], v[126:127], off offset:1024
	v_mul_f32_e32 v104, v104, v122
	v_mul_f32_e32 v105, v105, v122
	v_mul_f32_e32 v106, v106, v122
	v_mul_f32_e32 v107, v107, v122
	v_mul_f32_e32 v104, v72, v104
	v_mul_f32_e32 v105, v73, v105
	v_mul_f32_e32 v106, v74, v106
	v_mul_f32_e32 v107, v75, v107
	v_cvt_pk_bf16_f32 v124, v104, v105
	v_cvt_pk_bf16_f32 v125, v106, v107
	global_store_dwordx2 v[128:129], v[124:125], off offset:1024
	v_cvt_pk_bf16_f32 v126, v108, v109
	v_cvt_pk_bf16_f32 v127, v110, v111
	global_store_dwordx2 v[130:131], v[126:127], off offset:1536
	v_mul_f32_e32 v108, v108, v122
	v_mul_f32_e32 v109, v109, v122
	v_mul_f32_e32 v110, v110, v122
	v_mul_f32_e32 v111, v111, v122
	v_mul_f32_e32 v108, v76, v108
	v_mul_f32_e32 v109, v77, v109
	v_mul_f32_e32 v110, v78, v110
	v_mul_f32_e32 v111, v79, v111
	v_cvt_pk_bf16_f32 v124, v108, v109
	v_cvt_pk_bf16_f32 v125, v110, v111
	global_store_dwordx2 v[128:129], v[124:125], off offset:1536
	v_add_u32_e32 v132, 56, v0
	v_ashrrev_i32_e32 v133, 31, v132
	v_lshlrev_b64 v[138:139], 12, v[132:133]
	v_lshl_add_u64 v[2:3], v[134:135], 0, v[138:139]
	global_load_dwordx4 v[96:99], v[2:3], off offset:0
	global_load_dwordx4 v[100:103], v[2:3], off offset:1024
	global_load_dwordx4 v[104:107], v[2:3], off offset:2048
	global_load_dwordx4 v[108:111], v[2:3], off offset:3072
	v_add_u32_e32 v132, 48, v0
	v_ashrrev_i32_e32 v133, 31, v132
	v_lshlrev_b64 v[138:139], 11, v[132:133]
	v_lshl_add_u64 v[128:129], v[6:7], 0, v[138:139]
	v_lshl_add_u64 v[130:131], v[136:137], 0, v[138:139]
	s_waitcnt vmcnt(12)
	v_mul_f32_e32 v112, v81, v81
	v_mul_f32_e32 v113, v85, v85
	v_mul_f32_e32 v114, v89, v89
	v_mul_f32_e32 v115, v93, v93
	v_fmac_f32_e32 v112, v80, v80
	v_fmac_f32_e32 v113, v84, v84
	v_fmac_f32_e32 v114, v88, v88
	v_fmac_f32_e32 v115, v92, v92
	v_fmac_f32_e32 v112, v82, v82
	v_fmac_f32_e32 v113, v86, v86
	v_fmac_f32_e32 v114, v90, v90
	v_fmac_f32_e32 v115, v94, v94
	v_fmac_f32_e32 v112, v83, v83
	v_fmac_f32_e32 v113, v87, v87
	v_fmac_f32_e32 v114, v91, v91
	v_fmac_f32_e32 v115, v95, v95
	v_add_f32_e32 v116, v112, v113
	v_add_f32_e32 v116, v116, v114
	v_add_f32_e32 v116, v116, v115
	ds_bpermute_b32 v117, v14, v116
	s_waitcnt lgkmcnt(0)
	v_add_f32_e32 v116, v116, v117
	ds_bpermute_b32 v117, v15, v116
	s_waitcnt lgkmcnt(0)
	v_add_f32_e32 v116, v116, v117
	ds_bpermute_b32 v117, v16, v116
	s_waitcnt lgkmcnt(0)
	v_add_f32_e32 v116, v116, v117
	ds_bpermute_b32 v117, v17, v116
	s_waitcnt lgkmcnt(0)
	v_add_f32_e32 v116, v116, v117
	ds_bpermute_b32 v117, v18, v116
	s_waitcnt lgkmcnt(0)
	v_add_f32_e32 v116, v116, v117
	ds_bpermute_b32 v117, v19, v116
	s_waitcnt lgkmcnt(0)
	v_add_f32_e32 v116, v116, v117
	v_fmamk_f32 v116, v116, 0x3a800000, v217
	v_mul_f32_e32 v117, 0x4f800000, v116
	v_cmp_gt_f32_e32 vcc, s36, v116
	s_nop 1
	v_cndmask_b32_e32 v116, v116, v117, vcc
	v_sqrt_f32_e32 v117, v116
	s_nop 0
	v_add_u32_e32 v118, -1, v117
	v_add_u32_e32 v119, 1, v117
	v_fma_f32 v120, -v118, v117, v116
	v_fma_f32 v121, -v119, v117, v116
	v_cmp_ge_f32_e64 s[0:1], 0, v120
	s_nop 1
	v_cndmask_b32_e64 v117, v117, v118, s[0:1]
	v_cmp_lt_f32_e64 s[0:1], 0, v121
	s_nop 1
	v_cndmask_b32_e64 v117, v117, v119, s[0:1]
	v_mul_f32_e32 v118, 0x37800000, v117
	v_cndmask_b32_e32 v117, v117, v118, vcc
	v_cmp_class_f32_e32 vcc, v116, v218
	s_nop 1
	v_cndmask_b32_e32 v116, v117, v116, vcc
	v_div_scale_f32 v117, s[0:1], v116, v116, 1.0
	v_rcp_f32_e32 v119, v117
	v_div_scale_f32 v118, vcc, 1.0, v116, 1.0
	v_fma_f32 v120, -v117, v119, 1.0
	v_fmac_f32_e32 v119, v120, v119
	v_mul_f32_e32 v120, v118, v119
	v_fma_f32 v121, -v117, v120, v118
	v_fmac_f32_e32 v120, v121, v119
	v_fma_f32 v117, -v117, v120, v118
	v_div_fmas_f32 v117, v117, v119, v120
	v_div_fixup_f32 v122, v117, v116, 1.0
	v_cvt_pk_bf16_f32 v126, v80, v81
	v_cvt_pk_bf16_f32 v127, v82, v83
	global_store_dwordx2 v[130:131], v[126:127], off offset:0
	v_mul_f32_e32 v80, v80, v122
	v_mul_f32_e32 v81, v81, v122
	v_mul_f32_e32 v82, v82, v122
	v_mul_f32_e32 v83, v83, v122
	v_mul_f32_e32 v80, v64, v80
	v_mul_f32_e32 v81, v65, v81
	v_mul_f32_e32 v82, v66, v82
	v_mul_f32_e32 v83, v67, v83
	v_cvt_pk_bf16_f32 v124, v80, v81
	v_cvt_pk_bf16_f32 v125, v82, v83
	global_store_dwordx2 v[128:129], v[124:125], off offset:0
	v_cvt_pk_bf16_f32 v126, v84, v85
	v_cvt_pk_bf16_f32 v127, v86, v87
	global_store_dwordx2 v[130:131], v[126:127], off offset:512
	v_mul_f32_e32 v84, v84, v122
	v_mul_f32_e32 v85, v85, v122
	v_mul_f32_e32 v86, v86, v122
	v_mul_f32_e32 v87, v87, v122
	v_mul_f32_e32 v84, v68, v84
	v_mul_f32_e32 v85, v69, v85
	v_mul_f32_e32 v86, v70, v86
	v_mul_f32_e32 v87, v71, v87
	v_cvt_pk_bf16_f32 v124, v84, v85
	v_cvt_pk_bf16_f32 v125, v86, v87
	global_store_dwordx2 v[128:129], v[124:125], off offset:512
	v_cvt_pk_bf16_f32 v126, v88, v89
	v_cvt_pk_bf16_f32 v127, v90, v91
	global_store_dwordx2 v[130:131], v[126:127], off offset:1024
	v_mul_f32_e32 v88, v88, v122
	v_mul_f32_e32 v89, v89, v122
	v_mul_f32_e32 v90, v90, v122
	v_mul_f32_e32 v91, v91, v122
	v_mul_f32_e32 v88, v72, v88
	v_mul_f32_e32 v89, v73, v89
	v_mul_f32_e32 v90, v74, v90
	v_mul_f32_e32 v91, v75, v91
	v_cvt_pk_bf16_f32 v124, v88, v89
	v_cvt_pk_bf16_f32 v125, v90, v91
	global_store_dwordx2 v[128:129], v[124:125], off offset:1024
	v_cvt_pk_bf16_f32 v126, v92, v93
	v_cvt_pk_bf16_f32 v127, v94, v95
	global_store_dwordx2 v[130:131], v[126:127], off offset:1536
	v_mul_f32_e32 v92, v92, v122
	v_mul_f32_e32 v93, v93, v122
	v_mul_f32_e32 v94, v94, v122
	v_mul_f32_e32 v95, v95, v122
	v_mul_f32_e32 v92, v76, v92
	v_mul_f32_e32 v93, v77, v93
	v_mul_f32_e32 v94, v78, v94
	v_mul_f32_e32 v95, v79, v95
	v_cvt_pk_bf16_f32 v124, v92, v93
	v_cvt_pk_bf16_f32 v125, v94, v95
	global_store_dwordx2 v[128:129], v[124:125], off offset:1536
	v_add_u32_e32 v132, 56, v0
	v_ashrrev_i32_e32 v133, 31, v132
	v_lshlrev_b64 v[138:139], 11, v[132:133]
	v_lshl_add_u64 v[128:129], v[6:7], 0, v[138:139]
	v_lshl_add_u64 v[130:131], v[136:137], 0, v[138:139]
	s_waitcnt vmcnt(8)
	v_mul_f32_e32 v112, v97, v97
	v_mul_f32_e32 v113, v101, v101
	v_mul_f32_e32 v114, v105, v105
	v_mul_f32_e32 v115, v109, v109
	v_fmac_f32_e32 v112, v96, v96
	v_fmac_f32_e32 v113, v100, v100
	v_fmac_f32_e32 v114, v104, v104
	v_fmac_f32_e32 v115, v108, v108
	v_fmac_f32_e32 v112, v98, v98
	v_fmac_f32_e32 v113, v102, v102
	v_fmac_f32_e32 v114, v106, v106
	v_fmac_f32_e32 v115, v110, v110
	v_fmac_f32_e32 v112, v99, v99
	v_fmac_f32_e32 v113, v103, v103
	v_fmac_f32_e32 v114, v107, v107
	v_fmac_f32_e32 v115, v111, v111
	v_add_f32_e32 v116, v112, v113
	v_add_f32_e32 v116, v116, v114
	v_add_f32_e32 v116, v116, v115
	ds_bpermute_b32 v117, v14, v116
	s_waitcnt lgkmcnt(0)
	v_add_f32_e32 v116, v116, v117
	ds_bpermute_b32 v117, v15, v116
	s_waitcnt lgkmcnt(0)
	v_add_f32_e32 v116, v116, v117
	ds_bpermute_b32 v117, v16, v116
	s_waitcnt lgkmcnt(0)
	v_add_f32_e32 v116, v116, v117
	ds_bpermute_b32 v117, v17, v116
	s_waitcnt lgkmcnt(0)
	v_add_f32_e32 v116, v116, v117
	ds_bpermute_b32 v117, v18, v116
	s_waitcnt lgkmcnt(0)
	v_add_f32_e32 v116, v116, v117
	ds_bpermute_b32 v117, v19, v116
	s_waitcnt lgkmcnt(0)
	v_add_f32_e32 v116, v116, v117
	v_fmamk_f32 v116, v116, 0x3a800000, v217
	v_mul_f32_e32 v117, 0x4f800000, v116
	v_cmp_gt_f32_e32 vcc, s36, v116
	s_nop 1
	v_cndmask_b32_e32 v116, v116, v117, vcc
	v_sqrt_f32_e32 v117, v116
	s_nop 0
	v_add_u32_e32 v118, -1, v117
	v_add_u32_e32 v119, 1, v117
	v_fma_f32 v120, -v118, v117, v116
	v_fma_f32 v121, -v119, v117, v116
	v_cmp_ge_f32_e64 s[0:1], 0, v120
	s_nop 1
	v_cndmask_b32_e64 v117, v117, v118, s[0:1]
	v_cmp_lt_f32_e64 s[0:1], 0, v121
	s_nop 1
	v_cndmask_b32_e64 v117, v117, v119, s[0:1]
	v_mul_f32_e32 v118, 0x37800000, v117
	v_cndmask_b32_e32 v117, v117, v118, vcc
	v_cmp_class_f32_e32 vcc, v116, v218
	s_nop 1
	v_cndmask_b32_e32 v116, v117, v116, vcc
	v_div_scale_f32 v117, s[0:1], v116, v116, 1.0
	v_rcp_f32_e32 v119, v117
	v_div_scale_f32 v118, vcc, 1.0, v116, 1.0
	v_fma_f32 v120, -v117, v119, 1.0
	v_fmac_f32_e32 v119, v120, v119
	v_mul_f32_e32 v120, v118, v119
	v_fma_f32 v121, -v117, v120, v118
	v_fmac_f32_e32 v120, v121, v119
	v_fma_f32 v117, -v117, v120, v118
	v_div_fmas_f32 v117, v117, v119, v120
	v_div_fixup_f32 v122, v117, v116, 1.0
	v_cvt_pk_bf16_f32 v126, v96, v97
	v_cvt_pk_bf16_f32 v127, v98, v99
	global_store_dwordx2 v[130:131], v[126:127], off offset:0
	v_mul_f32_e32 v96, v96, v122
	v_mul_f32_e32 v97, v97, v122
	v_mul_f32_e32 v98, v98, v122
	v_mul_f32_e32 v99, v99, v122
	v_mul_f32_e32 v96, v64, v96
	v_mul_f32_e32 v97, v65, v97
	v_mul_f32_e32 v98, v66, v98
	v_mul_f32_e32 v99, v67, v99
	v_cvt_pk_bf16_f32 v124, v96, v97
	v_cvt_pk_bf16_f32 v125, v98, v99
	global_store_dwordx2 v[128:129], v[124:125], off offset:0
	v_cvt_pk_bf16_f32 v126, v100, v101
	v_cvt_pk_bf16_f32 v127, v102, v103
	global_store_dwordx2 v[130:131], v[126:127], off offset:512
	v_mul_f32_e32 v100, v100, v122
	v_mul_f32_e32 v101, v101, v122
	v_mul_f32_e32 v102, v102, v122
	v_mul_f32_e32 v103, v103, v122
	v_mul_f32_e32 v100, v68, v100
	v_mul_f32_e32 v101, v69, v101
	v_mul_f32_e32 v102, v70, v102
	v_mul_f32_e32 v103, v71, v103
	v_cvt_pk_bf16_f32 v124, v100, v101
	v_cvt_pk_bf16_f32 v125, v102, v103
	global_store_dwordx2 v[128:129], v[124:125], off offset:512
	v_cvt_pk_bf16_f32 v126, v104, v105
	v_cvt_pk_bf16_f32 v127, v106, v107
	global_store_dwordx2 v[130:131], v[126:127], off offset:1024
	v_mul_f32_e32 v104, v104, v122
	v_mul_f32_e32 v105, v105, v122
	v_mul_f32_e32 v106, v106, v122
	v_mul_f32_e32 v107, v107, v122
	v_mul_f32_e32 v104, v72, v104
	v_mul_f32_e32 v105, v73, v105
	v_mul_f32_e32 v106, v74, v106
	v_mul_f32_e32 v107, v75, v107
	v_cvt_pk_bf16_f32 v124, v104, v105
	v_cvt_pk_bf16_f32 v125, v106, v107
	global_store_dwordx2 v[128:129], v[124:125], off offset:1024
	v_cvt_pk_bf16_f32 v126, v108, v109
	v_cvt_pk_bf16_f32 v127, v110, v111
	global_store_dwordx2 v[130:131], v[126:127], off offset:1536
	v_mul_f32_e32 v108, v108, v122
	v_mul_f32_e32 v109, v109, v122
	v_mul_f32_e32 v110, v110, v122
	v_mul_f32_e32 v111, v111, v122
	v_mul_f32_e32 v108, v76, v108
	v_mul_f32_e32 v109, v77, v109
	v_mul_f32_e32 v110, v78, v110
	v_mul_f32_e32 v111, v79, v111
	v_cvt_pk_bf16_f32 v124, v108, v109
	v_cvt_pk_bf16_f32 v125, v110, v111
	global_store_dwordx2 v[128:129], v[124:125], off offset:1536
	s_mov_b32 s2, 64
	s_mov_b64 s[0:1], 0
	v_writelane_b32 v253, s0, 37
	s_mov_b64 s[12:13], 0
	s_mov_b64 s[84:85], -1
	v_writelane_b32 v253, s1, 38
	s_mov_b64 s[0:1], 0
	v_writelane_b32 v255, s0, 39
	s_mov_b32 s75, 0
	s_mov_b32 s16, -1
	s_mov_b32 s19, 0
	v_writelane_b32 v255, s1, 40
	s_mov_b32 s18, 0
	s_mov_b64 s[20:21], -1

.LBB0_651:
	s_or_b64 exec, exec, s[0:1]
	s_lshl_b32 s0, s80, 8
	s_or_b32 s0, s0, s58
	v_lshl_add_u32 v190, v3, 3, s0
	v_ashrrev_i32_e32 v3, 31, v2
	v_ashrrev_i32_e32 v189, 31, v188
	v_lshl_add_u64 v[148:149], v[2:3], 0, v[188:189]
	v_ashrrev_i32_e32 v191, 31, v190
	v_readlane_b32 s0, v253, 37
	v_lshlrev_b64 v[148:149], 10, v[148:149]
	v_lshl_add_u64 v[150:151], v[190:191], 0, s[64:65]
	v_readlane_b32 s1, v253, 38
	v_lshl_add_u64 v[194:195], v[150:151], 0, v[148:149]
	v_lshl_add_u64 v[202:203], v[194:195], 1, s[12:13]
	v_lshl_add_u64 v[136:137], v[190:191], 2, s[0:1]
	s_mov_b32 s0, 0x8000
	v_add_co_u32_e32 v148, vcc, s0, v202
	s_mov_b32 s0, 0x10000
	s_nop 0
	v_addc_co_u32_e32 v149, vcc, 0, v203, vcc
	global_load_dwordx4 v[140:143], v[136:137], off offset:16
	global_load_dwordx4 v[144:147], v[136:137], off
	global_load_dwordx4 v[132:135], v[136:137], off offset:528
	s_nop 0
	global_load_dwordx4 v[136:139], v[136:137], off offset:512
	s_nop 0
	global_load_dwordx4 v[160:163], v[202:203], off
	global_load_dwordx4 v[168:171], v[202:203], off offset:256
	global_load_dwordx4 v[172:175], v[148:149], off
	global_load_dwordx4 v[176:179], v[148:149], off offset:256
	v_add_co_u32_e32 v148, vcc, s0, v202
	s_mov_b32 s0, 0x18000
	s_nop 0
	v_addc_co_u32_e32 v149, vcc, 0, v203, vcc
	global_load_dwordx4 v[180:183], v[148:149], off
	global_load_dwordx4 v[164:167], v[148:149], off offset:256
	v_add_co_u32_e32 v148, vcc, s0, v202
	s_ashr_i32 s83, s82, 31
	s_nop 0
	v_addc_co_u32_e32 v149, vcc, 0, v203, vcc
	global_load_dwordx4 v[152:155], v[148:149], off
	s_nop 0
	global_load_dwordx4 v[148:151], v[148:149], off offset:256
	s_lshl_b64 s[0:1], s[82:83], 2
	s_waitcnt vmcnt(12)
	s_add_u32 s2, s49, s0
	s_addc_u32 s3, s60, s1
	s_waitcnt lgkmcnt(0)
	s_barrier
	s_mov_b64 s[0:1], exec
	v_readlane_b32 s6, v251, 5
	v_readlane_b32 s7, v251, 6
	s_and_b64 s[6:7], s[0:1], s[6:7]
	s_mov_b64 exec, s[6:7]
	s_cbranch_execz .LBB0_673
	v_mov_b64_e32 v[156:157], s[2:3]
	flat_atomic_add v[156:157], v220
	s_mov_b32 s81, 0x1000000
	s_mov_b64 s[6:7], 0
	s_branch .LBB0_662

.LBB0_1127:
	v_readlane_b32 s18, v253, 31
	v_readlane_b32 s50, v253, 17
	s_cmp_lg_u32 s18, 18
	v_readlane_b32 s48, v253, 16
	v_readlane_b32 s51, v253, 18
	s_cbranch_scc1 .LBB0_1130
	v_mov_b32_e32 v0, v216
	s_mov_b64 s[0:1], 0x5800000
	v_and_b32_e32 v4, 63, v0
	v_ashrrev_i32_e32 v5, 6, v0
	v_xor_b32_e32 v0, 1, v219
	v_cmp_lt_i32_e32 vcc, v0, v223
	s_mov_b32 s2, 0
	s_nop 0
	v_cndmask_b32_e32 v0, v219, v0, vcc
	v_lshlrev_b32_e32 v30, 2, v0
	v_xor_b32_e32 v0, 2, v219
	v_cmp_lt_i32_e32 vcc, v0, v223
	s_nop 1
	v_cndmask_b32_e32 v0, v219, v0, vcc
	v_lshlrev_b32_e32 v31, 2, v0
	v_xor_b32_e32 v0, 4, v219
	v_cmp_lt_i32_e32 vcc, v0, v223
	s_nop 1
	v_cndmask_b32_e32 v0, v219, v0, vcc
	v_lshlrev_b32_e32 v32, 2, v0
	v_xor_b32_e32 v0, 8, v219
	v_cmp_lt_i32_e32 vcc, v0, v223
	s_nop 1
	v_cndmask_b32_e32 v0, v219, v0, vcc
	v_cmp_lt_i32_e32 vcc, v221, v223
	v_lshlrev_b32_e32 v33, 2, v0
	s_nop 0
	v_cndmask_b32_e32 v0, v219, v221, vcc
	v_cmp_lt_i32_e32 vcc, v224, v223
	v_lshlrev_b32_e32 v34, 2, v0
	s_nop 0
	v_cndmask_b32_e32 v0, v219, v224, vcc
	v_lshlrev_b32_e32 v35, 2, v0
	v_lshlrev_b32_e32 v0, 3, v4
	v_lshl_add_u64 v[2:3], s[82:83], 0, v[0:1]
	v_lshl_add_u64 v[18:19], v[2:3], 0, s[0:1]
	s_mov_b64 s[0:1], 0x1b000000
	v_lshl_add_u64 v[24:25], v[2:3], 0, s[0:1]
	v_readlane_b32 s0, v253, 19
	v_readlane_b32 s1, v253, 21
	s_lshl_b32 s0, s0, 8
	s_lshl_b32 s1, s1, 6
	v_lshlrev_b32_e32 v0, 4, v4
	s_add_i32 s1, s1, s0
	v_readlane_b32 s0, v253, 24
	v_lshl_add_u64 v[20:21], s[52:53], 0, v[0:1]
	v_lshl_add_u64 v[22:23], s[58:59], 0, v[0:1]
	v_add_u32_e32 v0, s1, v5
	s_lshl_b32 s0, s0, 8
	v_subrev_u32_e32 v0, s0, v0
	v_readlane_b32 s0, v253, 20
	s_lshl_b32 s0, s0, 6
	s_nop 0
	v_subrev_u32_e32 v0, s0, v0
	v_readlane_b32 s0, v253, 32
	s_nop 1
	v_subrev_u32_e32 v0, s0, v0
	v_add_co_u32_e32 v134, vcc, 0x4000000, v20
	s_nop 1
	v_addc_co_u32_e32 v135, vcc, 0, v21, vcc
	v_add_co_u32_e32 v136, vcc, 0x2000000, v24
	s_nop 1
	v_addc_co_u32_e32 v137, vcc, 0, v25, vcc
	global_load_dwordx4 v[64:67], v[22:23], off offset:0
	global_load_dwordx4 v[68:71], v[22:23], off offset:1024
	global_load_dwordx4 v[72:75], v[22:23], off offset:2048
	global_load_dwordx4 v[76:79], v[22:23], off offset:3072
	v_mov_b32_e32 v132, v0
	v_ashrrev_i32_e32 v133, 31, v132
	v_lshlrev_b64 v[138:139], 12, v[132:133]
	v_lshl_add_u64 v[2:3], v[134:135], 0, v[138:139]
	global_load_dwordx4 v[80:83], v[2:3], off offset:0
	global_load_dwordx4 v[84:87], v[2:3], off offset:1024
	global_load_dwordx4 v[88:91], v[2:3], off offset:2048
	global_load_dwordx4 v[92:95], v[2:3], off offset:3072
	v_add_u32_e32 v132, 8, v0
	v_ashrrev_i32_e32 v133, 31, v132
	v_lshlrev_b64 v[138:139], 12, v[132:133]
	v_lshl_add_u64 v[2:3], v[134:135], 0, v[138:139]
	global_load_dwordx4 v[96:99], v[2:3], off offset:0
	global_load_dwordx4 v[100:103], v[2:3], off offset:1024
	global_load_dwordx4 v[104:107], v[2:3], off offset:2048
	global_load_dwordx4 v[108:111], v[2:3], off offset:3072
	v_mov_b32_e32 v132, v0
	v_ashrrev_i32_e32 v133, 31, v132
	v_lshlrev_b64 v[138:139], 11, v[132:133]
	v_lshl_add_u64 v[128:129], v[18:19], 0, v[138:139]
	v_lshl_add_u64 v[130:131], v[136:137], 0, v[138:139]
	s_waitcnt vmcnt(4)
	v_mul_f32_e32 v112, v81, v81
	v_mul_f32_e32 v113, v85, v85
	v_mul_f32_e32 v114, v89, v89
	v_mul_f32_e32 v115, v93, v93
	v_fmac_f32_e32 v112, v80, v80
	v_fmac_f32_e32 v113, v84, v84
	v_fmac_f32_e32 v114, v88, v88
	v_fmac_f32_e32 v115, v92, v92
	v_fmac_f32_e32 v112, v82, v82
	v_fmac_f32_e32 v113, v86, v86
	v_fmac_f32_e32 v114, v90, v90
	v_fmac_f32_e32 v115, v94, v94
	v_fmac_f32_e32 v112, v83, v83
	v_fmac_f32_e32 v113, v87, v87
	v_fmac_f32_e32 v114, v91, v91
	v_fmac_f32_e32 v115, v95, v95
	v_add_f32_e32 v116, v112, v113
	v_add_f32_e32 v116, v116, v114
	v_add_f32_e32 v116, v116, v115
	ds_bpermute_b32 v117, v30, v116
	s_waitcnt lgkmcnt(0)
	v_add_f32_e32 v116, v116, v117
	ds_bpermute_b32 v117, v31, v116
	s_waitcnt lgkmcnt(0)
	v_add_f32_e32 v116, v116, v117
	ds_bpermute_b32 v117, v32, v116
	s_waitcnt lgkmcnt(0)
	v_add_f32_e32 v116, v116, v117
	ds_bpermute_b32 v117, v33, v116
	s_waitcnt lgkmcnt(0)
	v_add_f32_e32 v116, v116, v117
	ds_bpermute_b32 v117, v34, v116
	s_waitcnt lgkmcnt(0)
	v_add_f32_e32 v116, v116, v117
	ds_bpermute_b32 v117, v35, v116
	s_waitcnt lgkmcnt(0)
	v_add_f32_e32 v116, v116, v117
	v_fmamk_f32 v116, v116, 0x3a800000, v217
	v_mul_f32_e32 v117, 0x4f800000, v116
	v_cmp_gt_f32_e32 vcc, s36, v116
	s_nop 1
	v_cndmask_b32_e32 v116, v116, v117, vcc
	v_sqrt_f32_e32 v117, v116
	s_nop 0
	v_add_u32_e32 v118, -1, v117
	v_add_u32_e32 v119, 1, v117
	v_fma_f32 v120, -v118, v117, v116
	v_fma_f32 v121, -v119, v117, v116
	v_cmp_ge_f32_e64 s[0:1], 0, v120
	s_nop 1
	v_cndmask_b32_e64 v117, v117, v118, s[0:1]
	v_cmp_lt_f32_e64 s[0:1], 0, v121
	s_nop 1
	v_cndmask_b32_e64 v117, v117, v119, s[0:1]
	v_mul_f32_e32 v118, 0x37800000, v117
	v_cndmask_b32_e32 v117, v117, v118, vcc
	v_cmp_class_f32_e32 vcc, v116, v218
	s_nop 1
	v_cndmask_b32_e32 v116, v117, v116, vcc
	v_div_scale_f32 v117, s[0:1], v116, v116, 1.0
	v_rcp_f32_e32 v119, v117
	v_div_scale_f32 v118, vcc, 1.0, v116, 1.0
	v_fma_f32 v120, -v117, v119, 1.0
	v_fmac_f32_e32 v119, v120, v119
	v_mul_f32_e32 v120, v118, v119
	v_fma_f32 v121, -v117, v120, v118
	v_fmac_f32_e32 v120, v121, v119
	v_fma_f32 v117, -v117, v120, v118
	v_div_fmas_f32 v117, v117, v119, v120
	v_div_fixup_f32 v122, v117, v116, 1.0
	v_cvt_pk_bf16_f32 v126, v80, v81
	v_cvt_pk_bf16_f32 v127, v82, v83
	global_store_dwordx2 v[130:131], v[126:127], off offset:0
	v_mul_f32_e32 v80, v80, v122
	v_mul_f32_e32 v81, v81, v122
	v_mul_f32_e32 v82, v82, v122
	v_mul_f32_e32 v83, v83, v122
	v_mul_f32_e32 v80, v64, v80
	v_mul_f32_e32 v81, v65, v81
	v_mul_f32_e32 v82, v66, v82
	v_mul_f32_e32 v83, v67, v83
	v_cvt_pk_bf16_f32 v124, v80, v81
	v_cvt_pk_bf16_f32 v125, v82, v83
	global_store_dwordx2 v[128:129], v[124:125], off offset:0
	v_cvt_pk_bf16_f32 v126, v84, v85
	v_cvt_pk_bf16_f32 v127, v86, v87
	global_store_dwordx2 v[130:131], v[126:127], off offset:512
	v_mul_f32_e32 v84, v84, v122
	v_mul_f32_e32 v85, v85, v122
	v_mul_f32_e32 v86, v86, v122
	v_mul_f32_e32 v87, v87, v122
	v_mul_f32_e32 v84, v68, v84
	v_mul_f32_e32 v85, v69, v85
	v_mul_f32_e32 v86, v70, v86
	v_mul_f32_e32 v87, v71, v87
	v_cvt_pk_bf16_f32 v124, v84, v85
	v_cvt_pk_bf16_f32 v125, v86, v87
	global_store_dwordx2 v[128:129], v[124:125], off offset:512
	v_cvt_pk_bf16_f32 v126, v88, v89
	v_cvt_pk_bf16_f32 v127, v90, v91
	global_store_dwordx2 v[130:131], v[126:127], off offset:1024
	v_mul_f32_e32 v88, v88, v122
	v_mul_f32_e32 v89, v89, v122
	v_mul_f32_e32 v90, v90, v122
	v_mul_f32_e32 v91, v91, v122
	v_mul_f32_e32 v88, v72, v88
	v_mul_f32_e32 v89, v73, v89
	v_mul_f32_e32 v90, v74, v90
	v_mul_f32_e32 v91, v75, v91
	v_cvt_pk_bf16_f32 v124, v88, v89
	v_cvt_pk_bf16_f32 v125, v90, v91
	global_store_dwordx2 v[128:129], v[124:125], off offset:1024
	v_cvt_pk_bf16_f32 v126, v92, v93
	v_cvt_pk_bf16_f32 v127, v94, v95
	global_store_dwordx2 v[130:131], v[126:127], off offset:1536
	v_mul_f32_e32 v92, v92, v122
	v_mul_f32_e32 v93, v93, v122
	v_mul_f32_e32 v94, v94, v122
	v_mul_f32_e32 v95, v95, v122
	v_mul_f32_e32 v92, v76, v92
	v_mul_f32_e32 v93, v77, v93
	v_mul_f32_e32 v94, v78, v94
	v_mul_f32_e32 v95, v79, v95
	v_cvt_pk_bf16_f32 v124, v92, v93
	v_cvt_pk_bf16_f32 v125, v94, v95
	global_store_dwordx2 v[128:129], v[124:125], off offset:1536
	v_add_u32_e32 v132, 16, v0
	v_ashrrev_i32_e32 v133, 31, v132
	v_lshlrev_b64 v[138:139], 12, v[132:133]
	v_lshl_add_u64 v[2:3], v[134:135], 0, v[138:139]
	global_load_dwordx4 v[80:83], v[2:3], off offset:0
	global_load_dwordx4 v[84:87], v[2:3], off offset:1024
	global_load_dwordx4 v[88:91], v[2:3], off offset:2048
	global_load_dwordx4 v[92:95], v[2:3], off offset:3072
	v_add_u32_e32 v132, 8, v0
	v_ashrrev_i32_e32 v133, 31, v132
	v_lshlrev_b64 v[138:139], 11, v[132:133]
	v_lshl_add_u64 v[128:129], v[18:19], 0, v[138:139]
	v_lshl_add_u64 v[130:131], v[136:137], 0, v[138:139]
	s_waitcnt vmcnt(12)
	v_mul_f32_e32 v112, v97, v97
	v_mul_f32_e32 v113, v101, v101
	v_mul_f32_e32 v114, v105, v105
	v_mul_f32_e32 v115, v109, v109
	v_fmac_f32_e32 v112, v96, v96
	v_fmac_f32_e32 v113, v100, v100
	v_fmac_f32_e32 v114, v104, v104
	v_fmac_f32_e32 v115, v108, v108
	v_fmac_f32_e32 v112, v98, v98
	v_fmac_f32_e32 v113, v102, v102
	v_fmac_f32_e32 v114, v106, v106
	v_fmac_f32_e32 v115, v110, v110
	v_fmac_f32_e32 v112, v99, v99
	v_fmac_f32_e32 v113, v103, v103
	v_fmac_f32_e32 v114, v107, v107
	v_fmac_f32_e32 v115, v111, v111
	v_add_f32_e32 v116, v112, v113
	v_add_f32_e32 v116, v116, v114
	v_add_f32_e32 v116, v116, v115
	ds_bpermute_b32 v117, v30, v116
	s_waitcnt lgkmcnt(0)
	v_add_f32_e32 v116, v116, v117
	ds_bpermute_b32 v117, v31, v116
	s_waitcnt lgkmcnt(0)
	v_add_f32_e32 v116, v116, v117
	ds_bpermute_b32 v117, v32, v116
	s_waitcnt lgkmcnt(0)
	v_add_f32_e32 v116, v116, v117
	ds_bpermute_b32 v117, v33, v116
	s_waitcnt lgkmcnt(0)
	v_add_f32_e32 v116, v116, v117
	ds_bpermute_b32 v117, v34, v116
	s_waitcnt lgkmcnt(0)
	v_add_f32_e32 v116, v116, v117
	ds_bpermute_b32 v117, v35, v116
	s_waitcnt lgkmcnt(0)
	v_add_f32_e32 v116, v116, v117
	v_fmamk_f32 v116, v116, 0x3a800000, v217
	v_mul_f32_e32 v117, 0x4f800000, v116
	v_cmp_gt_f32_e32 vcc, s36, v116
	s_nop 1
	v_cndmask_b32_e32 v116, v116, v117, vcc
	v_sqrt_f32_e32 v117, v116
	s_nop 0
	v_add_u32_e32 v118, -1, v117
	v_add_u32_e32 v119, 1, v117
	v_fma_f32 v120, -v118, v117, v116
	v_fma_f32 v121, -v119, v117, v116
	v_cmp_ge_f32_e64 s[0:1], 0, v120
	s_nop 1
	v_cndmask_b32_e64 v117, v117, v118, s[0:1]
	v_cmp_lt_f32_e64 s[0:1], 0, v121
	s_nop 1
	v_cndmask_b32_e64 v117, v117, v119, s[0:1]
	v_mul_f32_e32 v118, 0x37800000, v117
	v_cndmask_b32_e32 v117, v117, v118, vcc
	v_cmp_class_f32_e32 vcc, v116, v218
	s_nop 1
	v_cndmask_b32_e32 v116, v117, v116, vcc
	v_div_scale_f32 v117, s[0:1], v116, v116, 1.0
	v_rcp_f32_e32 v119, v117
	v_div_scale_f32 v118, vcc, 1.0, v116, 1.0
	v_fma_f32 v120, -v117, v119, 1.0
	v_fmac_f32_e32 v119, v120, v119
	v_mul_f32_e32 v120, v118, v119
	v_fma_f32 v121, -v117, v120, v118
	v_fmac_f32_e32 v120, v121, v119
	v_fma_f32 v117, -v117, v120, v118
	v_div_fmas_f32 v117, v117, v119, v120
	v_div_fixup_f32 v122, v117, v116, 1.0
	v_cvt_pk_bf16_f32 v126, v96, v97
	v_cvt_pk_bf16_f32 v127, v98, v99
	global_store_dwordx2 v[130:131], v[126:127], off offset:0
	v_mul_f32_e32 v96, v96, v122
	v_mul_f32_e32 v97, v97, v122
	v_mul_f32_e32 v98, v98, v122
	v_mul_f32_e32 v99, v99, v122
	v_mul_f32_e32 v96, v64, v96
	v_mul_f32_e32 v97, v65, v97
	v_mul_f32_e32 v98, v66, v98
	v_mul_f32_e32 v99, v67, v99
	v_cvt_pk_bf16_f32 v124, v96, v97
	v_cvt_pk_bf16_f32 v125, v98, v99
	global_store_dwordx2 v[128:129], v[124:125], off offset:0
	v_cvt_pk_bf16_f32 v126, v100, v101
	v_cvt_pk_bf16_f32 v127, v102, v103
	global_store_dwordx2 v[130:131], v[126:127], off offset:512
	v_mul_f32_e32 v100, v100, v122
	v_mul_f32_e32 v101, v101, v122
	v_mul_f32_e32 v102, v102, v122
	v_mul_f32_e32 v103, v103, v122
	v_mul_f32_e32 v100, v68, v100
	v_mul_f32_e32 v101, v69, v101
	v_mul_f32_e32 v102, v70, v102
	v_mul_f32_e32 v103, v71, v103
	v_cvt_pk_bf16_f32 v124, v100, v101
	v_cvt_pk_bf16_f32 v125, v102, v103
	global_store_dwordx2 v[128:129], v[124:125], off offset:512
	v_cvt_pk_bf16_f32 v126, v104, v105
	v_cvt_pk_bf16_f32 v127, v106, v107
	global_store_dwordx2 v[130:131], v[126:127], off offset:1024
	v_mul_f32_e32 v104, v104, v122
	v_mul_f32_e32 v105, v105, v122
	v_mul_f32_e32 v106, v106, v122
	v_mul_f32_e32 v107, v107, v122
	v_mul_f32_e32 v104, v72, v104
	v_mul_f32_e32 v105, v73, v105
	v_mul_f32_e32 v106, v74, v106
	v_mul_f32_e32 v107, v75, v107
	v_cvt_pk_bf16_f32 v124, v104, v105
	v_cvt_pk_bf16_f32 v125, v106, v107
	global_store_dwordx2 v[128:129], v[124:125], off offset:1024
	v_cvt_pk_bf16_f32 v126, v108, v109
	v_cvt_pk_bf16_f32 v127, v110, v111
	global_store_dwordx2 v[130:131], v[126:127], off offset:1536
	v_mul_f32_e32 v108, v108, v122
	v_mul_f32_e32 v109, v109, v122
	v_mul_f32_e32 v110, v110, v122
	v_mul_f32_e32 v111, v111, v122
	v_mul_f32_e32 v108, v76, v108
	v_mul_f32_e32 v109, v77, v109
	v_mul_f32_e32 v110, v78, v110
	v_mul_f32_e32 v111, v79, v111
	v_cvt_pk_bf16_f32 v124, v108, v109
	v_cvt_pk_bf16_f32 v125, v110, v111
	global_store_dwordx2 v[128:129], v[124:125], off offset:1536
	v_add_u32_e32 v132, 24, v0
	v_ashrrev_i32_e32 v133, 31, v132
	v_lshlrev_b64 v[138:139], 12, v[132:133]
	v_lshl_add_u64 v[2:3], v[134:135], 0, v[138:139]
	global_load_dwordx4 v[96:99], v[2:3], off offset:0
	global_load_dwordx4 v[100:103], v[2:3], off offset:1024
	global_load_dwordx4 v[104:107], v[2:3], off offset:2048
	global_load_dwordx4 v[108:111], v[2:3], off offset:3072
	v_add_u32_e32 v132, 16, v0
	v_ashrrev_i32_e32 v133, 31, v132
	v_lshlrev_b64 v[138:139], 11, v[132:133]
	v_lshl_add_u64 v[128:129], v[18:19], 0, v[138:139]
	v_lshl_add_u64 v[130:131], v[136:137], 0, v[138:139]
	s_waitcnt vmcnt(12)
	v_mul_f32_e32 v112, v81, v81
	v_mul_f32_e32 v113, v85, v85
	v_mul_f32_e32 v114, v89, v89
	v_mul_f32_e32 v115, v93, v93
	v_fmac_f32_e32 v112, v80, v80
	v_fmac_f32_e32 v113, v84, v84
	v_fmac_f32_e32 v114, v88, v88
	v_fmac_f32_e32 v115, v92, v92
	v_fmac_f32_e32 v112, v82, v82
	v_fmac_f32_e32 v113, v86, v86
	v_fmac_f32_e32 v114, v90, v90
	v_fmac_f32_e32 v115, v94, v94
	v_fmac_f32_e32 v112, v83, v83
	v_fmac_f32_e32 v113, v87, v87
	v_fmac_f32_e32 v114, v91, v91
	v_fmac_f32_e32 v115, v95, v95
	v_add_f32_e32 v116, v112, v113
	v_add_f32_e32 v116, v116, v114
	v_add_f32_e32 v116, v116, v115
	ds_bpermute_b32 v117, v30, v116
	s_waitcnt lgkmcnt(0)
	v_add_f32_e32 v116, v116, v117
	ds_bpermute_b32 v117, v31, v116
	s_waitcnt lgkmcnt(0)
	v_add_f32_e32 v116, v116, v117
	ds_bpermute_b32 v117, v32, v116
	s_waitcnt lgkmcnt(0)
	v_add_f32_e32 v116, v116, v117
	ds_bpermute_b32 v117, v33, v116
	s_waitcnt lgkmcnt(0)
	v_add_f32_e32 v116, v116, v117
	ds_bpermute_b32 v117, v34, v116
	s_waitcnt lgkmcnt(0)
	v_add_f32_e32 v116, v116, v117
	ds_bpermute_b32 v117, v35, v116
	s_waitcnt lgkmcnt(0)
	v_add_f32_e32 v116, v116, v117
	v_fmamk_f32 v116, v116, 0x3a800000, v217
	v_mul_f32_e32 v117, 0x4f800000, v116
	v_cmp_gt_f32_e32 vcc, s36, v116
	s_nop 1
	v_cndmask_b32_e32 v116, v116, v117, vcc
	v_sqrt_f32_e32 v117, v116
	s_nop 0
	v_add_u32_e32 v118, -1, v117
	v_add_u32_e32 v119, 1, v117
	v_fma_f32 v120, -v118, v117, v116
	v_fma_f32 v121, -v119, v117, v116
	v_cmp_ge_f32_e64 s[0:1], 0, v120
	s_nop 1
	v_cndmask_b32_e64 v117, v117, v118, s[0:1]
	v_cmp_lt_f32_e64 s[0:1], 0, v121
	s_nop 1
	v_cndmask_b32_e64 v117, v117, v119, s[0:1]
	v_mul_f32_e32 v118, 0x37800000, v117
	v_cndmask_b32_e32 v117, v117, v118, vcc
	v_cmp_class_f32_e32 vcc, v116, v218
	s_nop 1
	v_cndmask_b32_e32 v116, v117, v116, vcc
	v_div_scale_f32 v117, s[0:1], v116, v116, 1.0
	v_rcp_f32_e32 v119, v117
	v_div_scale_f32 v118, vcc, 1.0, v116, 1.0
	v_fma_f32 v120, -v117, v119, 1.0
	v_fmac_f32_e32 v119, v120, v119
	v_mul_f32_e32 v120, v118, v119
	v_fma_f32 v121, -v117, v120, v118
	v_fmac_f32_e32 v120, v121, v119
	v_fma_f32 v117, -v117, v120, v118
	v_div_fmas_f32 v117, v117, v119, v120
	v_div_fixup_f32 v122, v117, v116, 1.0
	v_cvt_pk_bf16_f32 v126, v80, v81
	v_cvt_pk_bf16_f32 v127, v82, v83
	global_store_dwordx2 v[130:131], v[126:127], off offset:0
	v_mul_f32_e32 v80, v80, v122
	v_mul_f32_e32 v81, v81, v122
	v_mul_f32_e32 v82, v82, v122
	v_mul_f32_e32 v83, v83, v122
	v_mul_f32_e32 v80, v64, v80
	v_mul_f32_e32 v81, v65, v81
	v_mul_f32_e32 v82, v66, v82
	v_mul_f32_e32 v83, v67, v83
	v_cvt_pk_bf16_f32 v124, v80, v81
	v_cvt_pk_bf16_f32 v125, v82, v83
	global_store_dwordx2 v[128:129], v[124:125], off offset:0
	v_cvt_pk_bf16_f32 v126, v84, v85
	v_cvt_pk_bf16_f32 v127, v86, v87
	global_store_dwordx2 v[130:131], v[126:127], off offset:512
	v_mul_f32_e32 v84, v84, v122
	v_mul_f32_e32 v85, v85, v122
	v_mul_f32_e32 v86, v86, v122
	v_mul_f32_e32 v87, v87, v122
	v_mul_f32_e32 v84, v68, v84
	v_mul_f32_e32 v85, v69, v85
	v_mul_f32_e32 v86, v70, v86
	v_mul_f32_e32 v87, v71, v87
	v_cvt_pk_bf16_f32 v124, v84, v85
	v_cvt_pk_bf16_f32 v125, v86, v87
	global_store_dwordx2 v[128:129], v[124:125], off offset:512
	v_cvt_pk_bf16_f32 v126, v88, v89
	v_cvt_pk_bf16_f32 v127, v90, v91
	global_store_dwordx2 v[130:131], v[126:127], off offset:1024
	v_mul_f32_e32 v88, v88, v122
	v_mul_f32_e32 v89, v89, v122
	v_mul_f32_e32 v90, v90, v122
	v_mul_f32_e32 v91, v91, v122
	v_mul_f32_e32 v88, v72, v88
	v_mul_f32_e32 v89, v73, v89
	v_mul_f32_e32 v90, v74, v90
	v_mul_f32_e32 v91, v75, v91
	v_cvt_pk_bf16_f32 v124, v88, v89
	v_cvt_pk_bf16_f32 v125, v90, v91
	global_store_dwordx2 v[128:129], v[124:125], off offset:1024
	v_cvt_pk_bf16_f32 v126, v92, v93
	v_cvt_pk_bf16_f32 v127, v94, v95
	global_store_dwordx2 v[130:131], v[126:127], off offset:1536
	v_mul_f32_e32 v92, v92, v122
	v_mul_f32_e32 v93, v93, v122
	v_mul_f32_e32 v94, v94, v122
	v_mul_f32_e32 v95, v95, v122
	v_mul_f32_e32 v92, v76, v92
	v_mul_f32_e32 v93, v77, v93
	v_mul_f32_e32 v94, v78, v94
	v_mul_f32_e32 v95, v79, v95
	v_cvt_pk_bf16_f32 v124, v92, v93
	v_cvt_pk_bf16_f32 v125, v94, v95
	global_store_dwordx2 v[128:129], v[124:125], off offset:1536
	v_add_u32_e32 v132, 32, v0
	v_ashrrev_i32_e32 v133, 31, v132
	v_lshlrev_b64 v[138:139], 12, v[132:133]
	v_lshl_add_u64 v[2:3], v[134:135], 0, v[138:139]
	global_load_dwordx4 v[80:83], v[2:3], off offset:0
	global_load_dwordx4 v[84:87], v[2:3], off offset:1024
	global_load_dwordx4 v[88:91], v[2:3], off offset:2048
	global_load_dwordx4 v[92:95], v[2:3], off offset:3072
	v_add_u32_e32 v132, 24, v0
	v_ashrrev_i32_e32 v133, 31, v132
	v_lshlrev_b64 v[138:139], 11, v[132:133]
	v_lshl_add_u64 v[128:129], v[18:19], 0, v[138:139]
	v_lshl_add_u64 v[130:131], v[136:137], 0, v[138:139]
	s_waitcnt vmcnt(12)
	v_mul_f32_e32 v112, v97, v97
	v_mul_f32_e32 v113, v101, v101
	v_mul_f32_e32 v114, v105, v105
	v_mul_f32_e32 v115, v109, v109
	v_fmac_f32_e32 v112, v96, v96
	v_fmac_f32_e32 v113, v100, v100
	v_fmac_f32_e32 v114, v104, v104
	v_fmac_f32_e32 v115, v108, v108
	v_fmac_f32_e32 v112, v98, v98
	v_fmac_f32_e32 v113, v102, v102
	v_fmac_f32_e32 v114, v106, v106
	v_fmac_f32_e32 v115, v110, v110
	v_fmac_f32_e32 v112, v99, v99
	v_fmac_f32_e32 v113, v103, v103
	v_fmac_f32_e32 v114, v107, v107
	v_fmac_f32_e32 v115, v111, v111
	v_add_f32_e32 v116, v112, v113
	v_add_f32_e32 v116, v116, v114
	v_add_f32_e32 v116, v116, v115
	ds_bpermute_b32 v117, v30, v116
	s_waitcnt lgkmcnt(0)
	v_add_f32_e32 v116, v116, v117
	ds_bpermute_b32 v117, v31, v116
	s_waitcnt lgkmcnt(0)
	v_add_f32_e32 v116, v116, v117
	ds_bpermute_b32 v117, v32, v116
	s_waitcnt lgkmcnt(0)
	v_add_f32_e32 v116, v116, v117
	ds_bpermute_b32 v117, v33, v116
	s_waitcnt lgkmcnt(0)
	v_add_f32_e32 v116, v116, v117
	ds_bpermute_b32 v117, v34, v116
	s_waitcnt lgkmcnt(0)
	v_add_f32_e32 v116, v116, v117
	ds_bpermute_b32 v117, v35, v116
	s_waitcnt lgkmcnt(0)
	v_add_f32_e32 v116, v116, v117
	v_fmamk_f32 v116, v116, 0x3a800000, v217
	v_mul_f32_e32 v117, 0x4f800000, v116
	v_cmp_gt_f32_e32 vcc, s36, v116
	s_nop 1
	v_cndmask_b32_e32 v116, v116, v117, vcc
	v_sqrt_f32_e32 v117, v116
	s_nop 0
	v_add_u32_e32 v118, -1, v117
	v_add_u32_e32 v119, 1, v117
	v_fma_f32 v120, -v118, v117, v116
	v_fma_f32 v121, -v119, v117, v116
	v_cmp_ge_f32_e64 s[0:1], 0, v120
	s_nop 1
	v_cndmask_b32_e64 v117, v117, v118, s[0:1]
	v_cmp_lt_f32_e64 s[0:1], 0, v121
	s_nop 1
	v_cndmask_b32_e64 v117, v117, v119, s[0:1]
	v_mul_f32_e32 v118, 0x37800000, v117
	v_cndmask_b32_e32 v117, v117, v118, vcc
	v_cmp_class_f32_e32 vcc, v116, v218
	s_nop 1
	v_cndmask_b32_e32 v116, v117, v116, vcc
	v_div_scale_f32 v117, s[0:1], v116, v116, 1.0
	v_rcp_f32_e32 v119, v117
	v_div_scale_f32 v118, vcc, 1.0, v116, 1.0
	v_fma_f32 v120, -v117, v119, 1.0
	v_fmac_f32_e32 v119, v120, v119
	v_mul_f32_e32 v120, v118, v119
	v_fma_f32 v121, -v117, v120, v118
	v_fmac_f32_e32 v120, v121, v119
	v_fma_f32 v117, -v117, v120, v118
	v_div_fmas_f32 v117, v117, v119, v120
	v_div_fixup_f32 v122, v117, v116, 1.0
	v_cvt_pk_bf16_f32 v126, v96, v97
	v_cvt_pk_bf16_f32 v127, v98, v99
	global_store_dwordx2 v[130:131], v[126:127], off offset:0
	v_mul_f32_e32 v96, v96, v122
	v_mul_f32_e32 v97, v97, v122
	v_mul_f32_e32 v98, v98, v122
	v_mul_f32_e32 v99, v99, v122
	v_mul_f32_e32 v96, v64, v96
	v_mul_f32_e32 v97, v65, v97
	v_mul_f32_e32 v98, v66, v98
	v_mul_f32_e32 v99, v67, v99
	v_cvt_pk_bf16_f32 v124, v96, v97
	v_cvt_pk_bf16_f32 v125, v98, v99
	global_store_dwordx2 v[128:129], v[124:125], off offset:0
	v_cvt_pk_bf16_f32 v126, v100, v101
	v_cvt_pk_bf16_f32 v127, v102, v103
	global_store_dwordx2 v[130:131], v[126:127], off offset:512
	v_mul_f32_e32 v100, v100, v122
	v_mul_f32_e32 v101, v101, v122
	v_mul_f32_e32 v102, v102, v122
	v_mul_f32_e32 v103, v103, v122
	v_mul_f32_e32 v100, v68, v100
	v_mul_f32_e32 v101, v69, v101
	v_mul_f32_e32 v102, v70, v102
	v_mul_f32_e32 v103, v71, v103
	v_cvt_pk_bf16_f32 v124, v100, v101
	v_cvt_pk_bf16_f32 v125, v102, v103
	global_store_dwordx2 v[128:129], v[124:125], off offset:512
	v_cvt_pk_bf16_f32 v126, v104, v105
	v_cvt_pk_bf16_f32 v127, v106, v107
	global_store_dwordx2 v[130:131], v[126:127], off offset:1024
	v_mul_f32_e32 v104, v104, v122
	v_mul_f32_e32 v105, v105, v122
	v_mul_f32_e32 v106, v106, v122
	v_mul_f32_e32 v107, v107, v122
	v_mul_f32_e32 v104, v72, v104
	v_mul_f32_e32 v105, v73, v105
	v_mul_f32_e32 v106, v74, v106
	v_mul_f32_e32 v107, v75, v107
	v_cvt_pk_bf16_f32 v124, v104, v105
	v_cvt_pk_bf16_f32 v125, v106, v107
	global_store_dwordx2 v[128:129], v[124:125], off offset:1024
	v_cvt_pk_bf16_f32 v126, v108, v109
	v_cvt_pk_bf16_f32 v127, v110, v111
	global_store_dwordx2 v[130:131], v[126:127], off offset:1536
	v_mul_f32_e32 v108, v108, v122
	v_mul_f32_e32 v109, v109, v122
	v_mul_f32_e32 v110, v110, v122
	v_mul_f32_e32 v111, v111, v122
	v_mul_f32_e32 v108, v76, v108
	v_mul_f32_e32 v109, v77, v109
	v_mul_f32_e32 v110, v78, v110
	v_mul_f32_e32 v111, v79, v111
	v_cvt_pk_bf16_f32 v124, v108, v109
	v_cvt_pk_bf16_f32 v125, v110, v111
	global_store_dwordx2 v[128:129], v[124:125], off offset:1536
	v_add_u32_e32 v132, 40, v0
	v_ashrrev_i32_e32 v133, 31, v132
	v_lshlrev_b64 v[138:139], 12, v[132:133]
	v_lshl_add_u64 v[2:3], v[134:135], 0, v[138:139]
	global_load_dwordx4 v[96:99], v[2:3], off offset:0
	global_load_dwordx4 v[100:103], v[2:3], off offset:1024
	global_load_dwordx4 v[104:107], v[2:3], off offset:2048
	global_load_dwordx4 v[108:111], v[2:3], off offset:3072
	v_add_u32_e32 v132, 32, v0
	v_ashrrev_i32_e32 v133, 31, v132
	v_lshlrev_b64 v[138:139], 11, v[132:133]
	v_lshl_add_u64 v[128:129], v[18:19], 0, v[138:139]
	v_lshl_add_u64 v[130:131], v[136:137], 0, v[138:139]
	s_waitcnt vmcnt(12)
	v_mul_f32_e32 v112, v81, v81
	v_mul_f32_e32 v113, v85, v85
	v_mul_f32_e32 v114, v89, v89
	v_mul_f32_e32 v115, v93, v93
	v_fmac_f32_e32 v112, v80, v80
	v_fmac_f32_e32 v113, v84, v84
	v_fmac_f32_e32 v114, v88, v88
	v_fmac_f32_e32 v115, v92, v92
	v_fmac_f32_e32 v112, v82, v82
	v_fmac_f32_e32 v113, v86, v86
	v_fmac_f32_e32 v114, v90, v90
	v_fmac_f32_e32 v115, v94, v94
	v_fmac_f32_e32 v112, v83, v83
	v_fmac_f32_e32 v113, v87, v87
	v_fmac_f32_e32 v114, v91, v91
	v_fmac_f32_e32 v115, v95, v95
	v_add_f32_e32 v116, v112, v113
	v_add_f32_e32 v116, v116, v114
	v_add_f32_e32 v116, v116, v115
	ds_bpermute_b32 v117, v30, v116
	s_waitcnt lgkmcnt(0)
	v_add_f32_e32 v116, v116, v117
	ds_bpermute_b32 v117, v31, v116
	s_waitcnt lgkmcnt(0)
	v_add_f32_e32 v116, v116, v117
	ds_bpermute_b32 v117, v32, v116
	s_waitcnt lgkmcnt(0)
	v_add_f32_e32 v116, v116, v117
	ds_bpermute_b32 v117, v33, v116
	s_waitcnt lgkmcnt(0)
	v_add_f32_e32 v116, v116, v117
	ds_bpermute_b32 v117, v34, v116
	s_waitcnt lgkmcnt(0)
	v_add_f32_e32 v116, v116, v117
	ds_bpermute_b32 v117, v35, v116
	s_waitcnt lgkmcnt(0)
	v_add_f32_e32 v116, v116, v117
	v_fmamk_f32 v116, v116, 0x3a800000, v217
	v_mul_f32_e32 v117, 0x4f800000, v116
	v_cmp_gt_f32_e32 vcc, s36, v116
	s_nop 1
	v_cndmask_b32_e32 v116, v116, v117, vcc
	v_sqrt_f32_e32 v117, v116
	s_nop 0
	v_add_u32_e32 v118, -1, v117
	v_add_u32_e32 v119, 1, v117
	v_fma_f32 v120, -v118, v117, v116
	v_fma_f32 v121, -v119, v117, v116
	v_cmp_ge_f32_e64 s[0:1], 0, v120
	s_nop 1
	v_cndmask_b32_e64 v117, v117, v118, s[0:1]
	v_cmp_lt_f32_e64 s[0:1], 0, v121
	s_nop 1
	v_cndmask_b32_e64 v117, v117, v119, s[0:1]
	v_mul_f32_e32 v118, 0x37800000, v117
	v_cndmask_b32_e32 v117, v117, v118, vcc
	v_cmp_class_f32_e32 vcc, v116, v218
	s_nop 1
	v_cndmask_b32_e32 v116, v117, v116, vcc
	v_div_scale_f32 v117, s[0:1], v116, v116, 1.0
	v_rcp_f32_e32 v119, v117
	v_div_scale_f32 v118, vcc, 1.0, v116, 1.0
	v_fma_f32 v120, -v117, v119, 1.0
	v_fmac_f32_e32 v119, v120, v119
	v_mul_f32_e32 v120, v118, v119
	v_fma_f32 v121, -v117, v120, v118
	v_fmac_f32_e32 v120, v121, v119
	v_fma_f32 v117, -v117, v120, v118
	v_div_fmas_f32 v117, v117, v119, v120
	v_div_fixup_f32 v122, v117, v116, 1.0
	v_cvt_pk_bf16_f32 v126, v80, v81
	v_cvt_pk_bf16_f32 v127, v82, v83
	global_store_dwordx2 v[130:131], v[126:127], off offset:0
	v_mul_f32_e32 v80, v80, v122
	v_mul_f32_e32 v81, v81, v122
	v_mul_f32_e32 v82, v82, v122
	v_mul_f32_e32 v83, v83, v122
	v_mul_f32_e32 v80, v64, v80
	v_mul_f32_e32 v81, v65, v81
	v_mul_f32_e32 v82, v66, v82
	v_mul_f32_e32 v83, v67, v83
	v_cvt_pk_bf16_f32 v124, v80, v81
	v_cvt_pk_bf16_f32 v125, v82, v83
	global_store_dwordx2 v[128:129], v[124:125], off offset:0
	v_cvt_pk_bf16_f32 v126, v84, v85
	v_cvt_pk_bf16_f32 v127, v86, v87
	global_store_dwordx2 v[130:131], v[126:127], off offset:512
	v_mul_f32_e32 v84, v84, v122
	v_mul_f32_e32 v85, v85, v122
	v_mul_f32_e32 v86, v86, v122
	v_mul_f32_e32 v87, v87, v122
	v_mul_f32_e32 v84, v68, v84
	v_mul_f32_e32 v85, v69, v85
	v_mul_f32_e32 v86, v70, v86
	v_mul_f32_e32 v87, v71, v87
	v_cvt_pk_bf16_f32 v124, v84, v85
	v_cvt_pk_bf16_f32 v125, v86, v87
	global_store_dwordx2 v[128:129], v[124:125], off offset:512
	v_cvt_pk_bf16_f32 v126, v88, v89
	v_cvt_pk_bf16_f32 v127, v90, v91
	global_store_dwordx2 v[130:131], v[126:127], off offset:1024
	v_mul_f32_e32 v88, v88, v122
	v_mul_f32_e32 v89, v89, v122
	v_mul_f32_e32 v90, v90, v122
	v_mul_f32_e32 v91, v91, v122
	v_mul_f32_e32 v88, v72, v88
	v_mul_f32_e32 v89, v73, v89
	v_mul_f32_e32 v90, v74, v90
	v_mul_f32_e32 v91, v75, v91
	v_cvt_pk_bf16_f32 v124, v88, v89
	v_cvt_pk_bf16_f32 v125, v90, v91
	global_store_dwordx2 v[128:129], v[124:125], off offset:1024
	v_cvt_pk_bf16_f32 v126, v92, v93
	v_cvt_pk_bf16_f32 v127, v94, v95
	global_store_dwordx2 v[130:131], v[126:127], off offset:1536
	v_mul_f32_e32 v92, v92, v122
	v_mul_f32_e32 v93, v93, v122
	v_mul_f32_e32 v94, v94, v122
	v_mul_f32_e32 v95, v95, v122
	v_mul_f32_e32 v92, v76, v92
	v_mul_f32_e32 v93, v77, v93
	v_mul_f32_e32 v94, v78, v94
	v_mul_f32_e32 v95, v79, v95
	v_cvt_pk_bf16_f32 v124, v92, v93
	v_cvt_pk_bf16_f32 v125, v94, v95
	global_store_dwordx2 v[128:129], v[124:125], off offset:1536
	v_add_u32_e32 v132, 48, v0
	v_ashrrev_i32_e32 v133, 31, v132
	v_lshlrev_b64 v[138:139], 12, v[132:133]
	v_lshl_add_u64 v[2:3], v[134:135], 0, v[138:139]
	global_load_dwordx4 v[80:83], v[2:3], off offset:0
	global_load_dwordx4 v[84:87], v[2:3], off offset:1024
	global_load_dwordx4 v[88:91], v[2:3], off offset:2048
	global_load_dwordx4 v[92:95], v[2:3], off offset:3072
	v_add_u32_e32 v132, 40, v0
	v_ashrrev_i32_e32 v133, 31, v132
	v_lshlrev_b64 v[138:139], 11, v[132:133]
	v_lshl_add_u64 v[128:129], v[18:19], 0, v[138:139]
	v_lshl_add_u64 v[130:131], v[136:137], 0, v[138:139]
	s_waitcnt vmcnt(12)
	v_mul_f32_e32 v112, v97, v97
	v_mul_f32_e32 v113, v101, v101
	v_mul_f32_e32 v114, v105, v105
	v_mul_f32_e32 v115, v109, v109
	v_fmac_f32_e32 v112, v96, v96
	v_fmac_f32_e32 v113, v100, v100
	v_fmac_f32_e32 v114, v104, v104
	v_fmac_f32_e32 v115, v108, v108
	v_fmac_f32_e32 v112, v98, v98
	v_fmac_f32_e32 v113, v102, v102
	v_fmac_f32_e32 v114, v106, v106
	v_fmac_f32_e32 v115, v110, v110
	v_fmac_f32_e32 v112, v99, v99
	v_fmac_f32_e32 v113, v103, v103
	v_fmac_f32_e32 v114, v107, v107
	v_fmac_f32_e32 v115, v111, v111
	v_add_f32_e32 v116, v112, v113
	v_add_f32_e32 v116, v116, v114
	v_add_f32_e32 v116, v116, v115
	ds_bpermute_b32 v117, v30, v116
	s_waitcnt lgkmcnt(0)
	v_add_f32_e32 v116, v116, v117
	ds_bpermute_b32 v117, v31, v116
	s_waitcnt lgkmcnt(0)
	v_add_f32_e32 v116, v116, v117
	ds_bpermute_b32 v117, v32, v116
	s_waitcnt lgkmcnt(0)
	v_add_f32_e32 v116, v116, v117
	ds_bpermute_b32 v117, v33, v116
	s_waitcnt lgkmcnt(0)
	v_add_f32_e32 v116, v116, v117
	ds_bpermute_b32 v117, v34, v116
	s_waitcnt lgkmcnt(0)
	v_add_f32_e32 v116, v116, v117
	ds_bpermute_b32 v117, v35, v116
	s_waitcnt lgkmcnt(0)
	v_add_f32_e32 v116, v116, v117
	v_fmamk_f32 v116, v116, 0x3a800000, v217
	v_mul_f32_e32 v117, 0x4f800000, v116
	v_cmp_gt_f32_e32 vcc, s36, v116
	s_nop 1
	v_cndmask_b32_e32 v116, v116, v117, vcc
	v_sqrt_f32_e32 v117, v116
	s_nop 0
	v_add_u32_e32 v118, -1, v117
	v_add_u32_e32 v119, 1, v117
	v_fma_f32 v120, -v118, v117, v116
	v_fma_f32 v121, -v119, v117, v116
	v_cmp_ge_f32_e64 s[0:1], 0, v120
	s_nop 1
	v_cndmask_b32_e64 v117, v117, v118, s[0:1]
	v_cmp_lt_f32_e64 s[0:1], 0, v121
	s_nop 1
	v_cndmask_b32_e64 v117, v117, v119, s[0:1]
	v_mul_f32_e32 v118, 0x37800000, v117
	v_cndmask_b32_e32 v117, v117, v118, vcc
	v_cmp_class_f32_e32 vcc, v116, v218
	s_nop 1
	v_cndmask_b32_e32 v116, v117, v116, vcc
	v_div_scale_f32 v117, s[0:1], v116, v116, 1.0
	v_rcp_f32_e32 v119, v117
	v_div_scale_f32 v118, vcc, 1.0, v116, 1.0
	v_fma_f32 v120, -v117, v119, 1.0
	v_fmac_f32_e32 v119, v120, v119
	v_mul_f32_e32 v120, v118, v119
	v_fma_f32 v121, -v117, v120, v118
	v_fmac_f32_e32 v120, v121, v119
	v_fma_f32 v117, -v117, v120, v118
	v_div_fmas_f32 v117, v117, v119, v120
	v_div_fixup_f32 v122, v117, v116, 1.0
	v_cvt_pk_bf16_f32 v126, v96, v97
	v_cvt_pk_bf16_f32 v127, v98, v99
	global_store_dwordx2 v[130:131], v[126:127], off offset:0
	v_mul_f32_e32 v96, v96, v122
	v_mul_f32_e32 v97, v97, v122
	v_mul_f32_e32 v98, v98, v122
	v_mul_f32_e32 v99, v99, v122
	v_mul_f32_e32 v96, v64, v96
	v_mul_f32_e32 v97, v65, v97
	v_mul_f32_e32 v98, v66, v98
	v_mul_f32_e32 v99, v67, v99
	v_cvt_pk_bf16_f32 v124, v96, v97
	v_cvt_pk_bf16_f32 v125, v98, v99
	global_store_dwordx2 v[128:129], v[124:125], off offset:0
	v_cvt_pk_bf16_f32 v126, v100, v101
	v_cvt_pk_bf16_f32 v127, v102, v103
	global_store_dwordx2 v[130:131], v[126:127], off offset:512
	v_mul_f32_e32 v100, v100, v122
	v_mul_f32_e32 v101, v101, v122
	v_mul_f32_e32 v102, v102, v122
	v_mul_f32_e32 v103, v103, v122
	v_mul_f32_e32 v100, v68, v100
	v_mul_f32_e32 v101, v69, v101
	v_mul_f32_e32 v102, v70, v102
	v_mul_f32_e32 v103, v71, v103
	v_cvt_pk_bf16_f32 v124, v100, v101
	v_cvt_pk_bf16_f32 v125, v102, v103
	global_store_dwordx2 v[128:129], v[124:125], off offset:512
	v_cvt_pk_bf16_f32 v126, v104, v105
	v_cvt_pk_bf16_f32 v127, v106, v107
	global_store_dwordx2 v[130:131], v[126:127], off offset:1024
	v_mul_f32_e32 v104, v104, v122
	v_mul_f32_e32 v105, v105, v122
	v_mul_f32_e32 v106, v106, v122
	v_mul_f32_e32 v107, v107, v122
	v_mul_f32_e32 v104, v72, v104
	v_mul_f32_e32 v105, v73, v105
	v_mul_f32_e32 v106, v74, v106
	v_mul_f32_e32 v107, v75, v107
	v_cvt_pk_bf16_f32 v124, v104, v105
	v_cvt_pk_bf16_f32 v125, v106, v107
	global_store_dwordx2 v[128:129], v[124:125], off offset:1024
	v_cvt_pk_bf16_f32 v126, v108, v109
	v_cvt_pk_bf16_f32 v127, v110, v111
	global_store_dwordx2 v[130:131], v[126:127], off offset:1536
	v_mul_f32_e32 v108, v108, v122
	v_mul_f32_e32 v109, v109, v122
	v_mul_f32_e32 v110, v110, v122
	v_mul_f32_e32 v111, v111, v122
	v_mul_f32_e32 v108, v76, v108
	v_mul_f32_e32 v109, v77, v109
	v_mul_f32_e32 v110, v78, v110
	v_mul_f32_e32 v111, v79, v111
	v_cvt_pk_bf16_f32 v124, v108, v109
	v_cvt_pk_bf16_f32 v125, v110, v111
	global_store_dwordx2 v[128:129], v[124:125], off offset:1536
	v_add_u32_e32 v132, 56, v0
	v_ashrrev_i32_e32 v133, 31, v132
	v_lshlrev_b64 v[138:139], 12, v[132:133]
	v_lshl_add_u64 v[2:3], v[134:135], 0, v[138:139]
	global_load_dwordx4 v[96:99], v[2:3], off offset:0
	global_load_dwordx4 v[100:103], v[2:3], off offset:1024
	global_load_dwordx4 v[104:107], v[2:3], off offset:2048
	global_load_dwordx4 v[108:111], v[2:3], off offset:3072
	v_add_u32_e32 v132, 48, v0
	v_ashrrev_i32_e32 v133, 31, v132
	v_lshlrev_b64 v[138:139], 11, v[132:133]
	v_lshl_add_u64 v[128:129], v[18:19], 0, v[138:139]
	v_lshl_add_u64 v[130:131], v[136:137], 0, v[138:139]
	s_waitcnt vmcnt(12)
	v_mul_f32_e32 v112, v81, v81
	v_mul_f32_e32 v113, v85, v85
	v_mul_f32_e32 v114, v89, v89
	v_mul_f32_e32 v115, v93, v93
	v_fmac_f32_e32 v112, v80, v80
	v_fmac_f32_e32 v113, v84, v84
	v_fmac_f32_e32 v114, v88, v88
	v_fmac_f32_e32 v115, v92, v92
	v_fmac_f32_e32 v112, v82, v82
	v_fmac_f32_e32 v113, v86, v86
	v_fmac_f32_e32 v114, v90, v90
	v_fmac_f32_e32 v115, v94, v94
	v_fmac_f32_e32 v112, v83, v83
	v_fmac_f32_e32 v113, v87, v87
	v_fmac_f32_e32 v114, v91, v91
	v_fmac_f32_e32 v115, v95, v95
	v_add_f32_e32 v116, v112, v113
	v_add_f32_e32 v116, v116, v114
	v_add_f32_e32 v116, v116, v115
	ds_bpermute_b32 v117, v30, v116
	s_waitcnt lgkmcnt(0)
	v_add_f32_e32 v116, v116, v117
	ds_bpermute_b32 v117, v31, v116
	s_waitcnt lgkmcnt(0)
	v_add_f32_e32 v116, v116, v117
	ds_bpermute_b32 v117, v32, v116
	s_waitcnt lgkmcnt(0)
	v_add_f32_e32 v116, v116, v117
	ds_bpermute_b32 v117, v33, v116
	s_waitcnt lgkmcnt(0)
	v_add_f32_e32 v116, v116, v117
	ds_bpermute_b32 v117, v34, v116
	s_waitcnt lgkmcnt(0)
	v_add_f32_e32 v116, v116, v117
	ds_bpermute_b32 v117, v35, v116
	s_waitcnt lgkmcnt(0)
	v_add_f32_e32 v116, v116, v117
	v_fmamk_f32 v116, v116, 0x3a800000, v217
	v_mul_f32_e32 v117, 0x4f800000, v116
	v_cmp_gt_f32_e32 vcc, s36, v116
	s_nop 1
	v_cndmask_b32_e32 v116, v116, v117, vcc
	v_sqrt_f32_e32 v117, v116
	s_nop 0
	v_add_u32_e32 v118, -1, v117
	v_add_u32_e32 v119, 1, v117
	v_fma_f32 v120, -v118, v117, v116
	v_fma_f32 v121, -v119, v117, v116
	v_cmp_ge_f32_e64 s[0:1], 0, v120
	s_nop 1
	v_cndmask_b32_e64 v117, v117, v118, s[0:1]
	v_cmp_lt_f32_e64 s[0:1], 0, v121
	s_nop 1
	v_cndmask_b32_e64 v117, v117, v119, s[0:1]
	v_mul_f32_e32 v118, 0x37800000, v117
	v_cndmask_b32_e32 v117, v117, v118, vcc
	v_cmp_class_f32_e32 vcc, v116, v218
	s_nop 1
	v_cndmask_b32_e32 v116, v117, v116, vcc
	v_div_scale_f32 v117, s[0:1], v116, v116, 1.0
	v_rcp_f32_e32 v119, v117
	v_div_scale_f32 v118, vcc, 1.0, v116, 1.0
	v_fma_f32 v120, -v117, v119, 1.0
	v_fmac_f32_e32 v119, v120, v119
	v_mul_f32_e32 v120, v118, v119
	v_fma_f32 v121, -v117, v120, v118
	v_fmac_f32_e32 v120, v121, v119
	v_fma_f32 v117, -v117, v120, v118
	v_div_fmas_f32 v117, v117, v119, v120
	v_div_fixup_f32 v122, v117, v116, 1.0
	v_cvt_pk_bf16_f32 v126, v80, v81
	v_cvt_pk_bf16_f32 v127, v82, v83
	global_store_dwordx2 v[130:131], v[126:127], off offset:0
	v_mul_f32_e32 v80, v80, v122
	v_mul_f32_e32 v81, v81, v122
	v_mul_f32_e32 v82, v82, v122
	v_mul_f32_e32 v83, v83, v122
	v_mul_f32_e32 v80, v64, v80
	v_mul_f32_e32 v81, v65, v81
	v_mul_f32_e32 v82, v66, v82
	v_mul_f32_e32 v83, v67, v83
	v_cvt_pk_bf16_f32 v124, v80, v81
	v_cvt_pk_bf16_f32 v125, v82, v83
	global_store_dwordx2 v[128:129], v[124:125], off offset:0
	v_cvt_pk_bf16_f32 v126, v84, v85
	v_cvt_pk_bf16_f32 v127, v86, v87
	global_store_dwordx2 v[130:131], v[126:127], off offset:512
	v_mul_f32_e32 v84, v84, v122
	v_mul_f32_e32 v85, v85, v122
	v_mul_f32_e32 v86, v86, v122
	v_mul_f32_e32 v87, v87, v122
	v_mul_f32_e32 v84, v68, v84
	v_mul_f32_e32 v85, v69, v85
	v_mul_f32_e32 v86, v70, v86
	v_mul_f32_e32 v87, v71, v87
	v_cvt_pk_bf16_f32 v124, v84, v85
	v_cvt_pk_bf16_f32 v125, v86, v87
	global_store_dwordx2 v[128:129], v[124:125], off offset:512
	v_cvt_pk_bf16_f32 v126, v88, v89
	v_cvt_pk_bf16_f32 v127, v90, v91
	global_store_dwordx2 v[130:131], v[126:127], off offset:1024
	v_mul_f32_e32 v88, v88, v122
	v_mul_f32_e32 v89, v89, v122
	v_mul_f32_e32 v90, v90, v122
	v_mul_f32_e32 v91, v91, v122
	v_mul_f32_e32 v88, v72, v88
	v_mul_f32_e32 v89, v73, v89
	v_mul_f32_e32 v90, v74, v90
	v_mul_f32_e32 v91, v75, v91
	v_cvt_pk_bf16_f32 v124, v88, v89
	v_cvt_pk_bf16_f32 v125, v90, v91
	global_store_dwordx2 v[128:129], v[124:125], off offset:1024
	v_cvt_pk_bf16_f32 v126, v92, v93
	v_cvt_pk_bf16_f32 v127, v94, v95
	global_store_dwordx2 v[130:131], v[126:127], off offset:1536
	v_mul_f32_e32 v92, v92, v122
	v_mul_f32_e32 v93, v93, v122
	v_mul_f32_e32 v94, v94, v122
	v_mul_f32_e32 v95, v95, v122
	v_mul_f32_e32 v92, v76, v92
	v_mul_f32_e32 v93, v77, v93
	v_mul_f32_e32 v94, v78, v94
	v_mul_f32_e32 v95, v79, v95
	v_cvt_pk_bf16_f32 v124, v92, v93
	v_cvt_pk_bf16_f32 v125, v94, v95
	global_store_dwordx2 v[128:129], v[124:125], off offset:1536
	v_add_u32_e32 v132, 56, v0
	v_ashrrev_i32_e32 v133, 31, v132
	v_lshlrev_b64 v[138:139], 11, v[132:133]
	v_lshl_add_u64 v[128:129], v[18:19], 0, v[138:139]
	v_lshl_add_u64 v[130:131], v[136:137], 0, v[138:139]
	s_waitcnt vmcnt(8)
	v_mul_f32_e32 v112, v97, v97
	v_mul_f32_e32 v113, v101, v101
	v_mul_f32_e32 v114, v105, v105
	v_mul_f32_e32 v115, v109, v109
	v_fmac_f32_e32 v112, v96, v96
	v_fmac_f32_e32 v113, v100, v100
	v_fmac_f32_e32 v114, v104, v104
	v_fmac_f32_e32 v115, v108, v108
	v_fmac_f32_e32 v112, v98, v98
	v_fmac_f32_e32 v113, v102, v102
	v_fmac_f32_e32 v114, v106, v106
	v_fmac_f32_e32 v115, v110, v110
	v_fmac_f32_e32 v112, v99, v99
	v_fmac_f32_e32 v113, v103, v103
	v_fmac_f32_e32 v114, v107, v107
	v_fmac_f32_e32 v115, v111, v111
	v_add_f32_e32 v116, v112, v113
	v_add_f32_e32 v116, v116, v114
	v_add_f32_e32 v116, v116, v115
	ds_bpermute_b32 v117, v30, v116
	s_waitcnt lgkmcnt(0)
	v_add_f32_e32 v116, v116, v117
	ds_bpermute_b32 v117, v31, v116
	s_waitcnt lgkmcnt(0)
	v_add_f32_e32 v116, v116, v117
	ds_bpermute_b32 v117, v32, v116
	s_waitcnt lgkmcnt(0)
	v_add_f32_e32 v116, v116, v117
	ds_bpermute_b32 v117, v33, v116
	s_waitcnt lgkmcnt(0)
	v_add_f32_e32 v116, v116, v117
	ds_bpermute_b32 v117, v34, v116
	s_waitcnt lgkmcnt(0)
	v_add_f32_e32 v116, v116, v117
	ds_bpermute_b32 v117, v35, v116
	s_waitcnt lgkmcnt(0)
	v_add_f32_e32 v116, v116, v117
	v_fmamk_f32 v116, v116, 0x3a800000, v217
	v_mul_f32_e32 v117, 0x4f800000, v116
	v_cmp_gt_f32_e32 vcc, s36, v116
	s_nop 1
	v_cndmask_b32_e32 v116, v116, v117, vcc
	v_sqrt_f32_e32 v117, v116
	s_nop 0
	v_add_u32_e32 v118, -1, v117
	v_add_u32_e32 v119, 1, v117
	v_fma_f32 v120, -v118, v117, v116
	v_fma_f32 v121, -v119, v117, v116
	v_cmp_ge_f32_e64 s[0:1], 0, v120
	s_nop 1
	v_cndmask_b32_e64 v117, v117, v118, s[0:1]
	v_cmp_lt_f32_e64 s[0:1], 0, v121
	s_nop 1
	v_cndmask_b32_e64 v117, v117, v119, s[0:1]
	v_mul_f32_e32 v118, 0x37800000, v117
	v_cndmask_b32_e32 v117, v117, v118, vcc
	v_cmp_class_f32_e32 vcc, v116, v218
	s_nop 1
	v_cndmask_b32_e32 v116, v117, v116, vcc
	v_div_scale_f32 v117, s[0:1], v116, v116, 1.0
	v_rcp_f32_e32 v119, v117
	v_div_scale_f32 v118, vcc, 1.0, v116, 1.0
	v_fma_f32 v120, -v117, v119, 1.0
	v_fmac_f32_e32 v119, v120, v119
	v_mul_f32_e32 v120, v118, v119
	v_fma_f32 v121, -v117, v120, v118
	v_fmac_f32_e32 v120, v121, v119
	v_fma_f32 v117, -v117, v120, v118
	v_div_fmas_f32 v117, v117, v119, v120
	v_div_fixup_f32 v122, v117, v116, 1.0
	v_cvt_pk_bf16_f32 v126, v96, v97
	v_cvt_pk_bf16_f32 v127, v98, v99
	global_store_dwordx2 v[130:131], v[126:127], off offset:0
	v_mul_f32_e32 v96, v96, v122
	v_mul_f32_e32 v97, v97, v122
	v_mul_f32_e32 v98, v98, v122
	v_mul_f32_e32 v99, v99, v122
	v_mul_f32_e32 v96, v64, v96
	v_mul_f32_e32 v97, v65, v97
	v_mul_f32_e32 v98, v66, v98
	v_mul_f32_e32 v99, v67, v99
	v_cvt_pk_bf16_f32 v124, v96, v97
	v_cvt_pk_bf16_f32 v125, v98, v99
	global_store_dwordx2 v[128:129], v[124:125], off offset:0
	v_cvt_pk_bf16_f32 v126, v100, v101
	v_cvt_pk_bf16_f32 v127, v102, v103
	global_store_dwordx2 v[130:131], v[126:127], off offset:512
	v_mul_f32_e32 v100, v100, v122
	v_mul_f32_e32 v101, v101, v122
	v_mul_f32_e32 v102, v102, v122
	v_mul_f32_e32 v103, v103, v122
	v_mul_f32_e32 v100, v68, v100
	v_mul_f32_e32 v101, v69, v101
	v_mul_f32_e32 v102, v70, v102
	v_mul_f32_e32 v103, v71, v103
	v_cvt_pk_bf16_f32 v124, v100, v101
	v_cvt_pk_bf16_f32 v125, v102, v103
	global_store_dwordx2 v[128:129], v[124:125], off offset:512
	v_cvt_pk_bf16_f32 v126, v104, v105
	v_cvt_pk_bf16_f32 v127, v106, v107
	global_store_dwordx2 v[130:131], v[126:127], off offset:1024
	v_mul_f32_e32 v104, v104, v122
	v_mul_f32_e32 v105, v105, v122
	v_mul_f32_e32 v106, v106, v122
	v_mul_f32_e32 v107, v107, v122
	v_mul_f32_e32 v104, v72, v104
	v_mul_f32_e32 v105, v73, v105
	v_mul_f32_e32 v106, v74, v106
	v_mul_f32_e32 v107, v75, v107
	v_cvt_pk_bf16_f32 v124, v104, v105
	v_cvt_pk_bf16_f32 v125, v106, v107
	global_store_dwordx2 v[128:129], v[124:125], off offset:1024
	v_cvt_pk_bf16_f32 v126, v108, v109
	v_cvt_pk_bf16_f32 v127, v110, v111
	global_store_dwordx2 v[130:131], v[126:127], off offset:1536
	v_mul_f32_e32 v108, v108, v122
	v_mul_f32_e32 v109, v109, v122
	v_mul_f32_e32 v110, v110, v122
	v_mul_f32_e32 v111, v111, v122
	v_mul_f32_e32 v108, v76, v108
	v_mul_f32_e32 v109, v77, v109
	v_mul_f32_e32 v110, v78, v110
	v_mul_f32_e32 v111, v79, v111
	v_cvt_pk_bf16_f32 v124, v108, v109
	v_cvt_pk_bf16_f32 v125, v110, v111
	global_store_dwordx2 v[128:129], v[124:125], off offset:1536
	s_mov_b32 s2, 64
